# P10 sliding window: thread walks 12 consecutive 8-token blocks of its 4 columns (no halo re-reads, weights loaded once)
# speedup vs baseline: 1.0138x; 1.0075x over previous
.LBB0_1005:
	s_cmp_lt_i32 s34, 11
	s_cselect_b64 s[10:11], -1, 0
	s_and_b64 s[6:7], s[10:11], s[6:7]
	s_andn2_b64 vcc, exec, s[6:7]
	s_cbranch_vccnz .LBB0_1012
	v_lshl_or_b32 v1, s2, 9, v0
	s_waitcnt lgkmcnt(0)
	s_mov_b32 s3, 0x160000
	v_cmp_gt_i32_e32 vcc, s3, v1
	s_and_saveexec_b64 s[12:13], vcc
	s_cbranch_execz .LBB0_1011
	s_load_dword s3, s[0:1], 0xd8
	s_add_u32 s14, s70, 0x7900000
	s_addc_u32 s15, s71, 0
	s_add_u32 s16, s14, 0x2c00
	s_addc_u32 s17, s15, 0
	s_add_u32 s18, s70, 0x1600000
	s_addc_u32 s19, s71, 0
	s_mov_b32 s38, 0x2e8ba2e9
	v_mov_b32_e32 v216, 0
	v_mov_b32_e32 v217, 0
	v_mov_b32_e32 v110, v1
	s_waitcnt lgkmcnt(0)
	s_lshl_b32 s3, s3, 9
	s_mov_b32 s39, 0x1d900
	v_cmp_gt_u32_e32 vcc, s39, v110
	s_and_b64 exec, exec, vcc
	s_cbranch_execz .Lcv_done
.Lcv_task:
	v_mul_hi_u32 v2, v110, s38
	v_lshrrev_b32_e32 v2, 8, v2
	v_mul_u32_u24_e32 v3, 0x580, v2
	v_sub_u32_e32 v3, v110, v3
	v_lshlrev_b32_e32 v113, 3, v3
	v_mul_u32_u24_e32 v111, 12, v2
	v_add_u32_e32 v112, 12, v111
	v_min_u32_e32 v112, 0x400, v112
	v_lshlrev_b32_e32 v4, 4, v3
	v_add_u32_e32 v5, 0xb000, v4
	global_load_dwordx4 v[72:75], v5, s[54:55]
	global_load_dwordx4 v[76:79], v4, s[54:55]
	v_add_u32_e32 v5, 0x16000, v4
	global_load_dwordx4 v[80:83], v5, s[54:55]
	global_load_dwordx4 v[84:87], v4, s[56:57]
	v_add_u32_e32 v5, 0x10800, v4
	global_load_dwordx4 v[88:91], v5, s[54:55]
	v_add_u32_e32 v5, 0x5800, v4
	global_load_dwordx4 v[92:95], v5, s[54:55]
	v_add_u32_e32 v5, 0x1b800, v4
	global_load_dwordx4 v[96:99], v5, s[54:55]
	v_add_u32_e32 v5, 0x5800, v4
	global_load_dwordx4 v[100:103], v5, s[56:57]
	v_lshlrev_b32_e32 v5, 3, v111
	v_mul_u32_u24_e32 v6, 0x5800, v5
	v_add_u32_e32 v6, v6, v113
	v_mul_u32_u24_e32 v7, 0x2c00, v5
	v_add_u32_e32 v7, v7, v113
	v_and_b32_e32 v5, 0x1ff, v111
	v_cmp_eq_u32_e32 vcc, 0, v5
	s_nop 1
	v_add_u32_e32 v4, 0xffff5000, v6
	v_cndmask_b32_e32 v4, v4, v6, vcc
	global_load_dwordx2 v[52:53], v4, s[14:15]
	global_load_dwordx2 v[68:69], v4, s[16:17]
	v_add_u32_e32 v4, 0xffffa800, v6
	v_cndmask_b32_e32 v4, v4, v6, vcc
	global_load_dwordx2 v[54:55], v4, s[14:15]
	global_load_dwordx2 v[70:71], v4, s[16:17]
	v_lshlrev_b32_e32 v5, 3, v111
	v_mul_u32_u24_e32 v6, 0x5800, v5
	v_add_u32_e32 v6, v6, v113
	v_mul_u32_u24_e32 v7, 0x2c00, v5
	v_add_u32_e32 v7, v7, v113
	v_mov_b32_e32 v117, v7
	global_load_dwordx2 v[8:9], v6, s[14:15]
	global_load_dwordx2 v[24:25], v6, s[16:17]
	v_add_u32_e32 v6, 0x5800, v6
	global_load_dwordx2 v[10:11], v6, s[14:15]
	global_load_dwordx2 v[26:27], v6, s[16:17]
	v_add_u32_e32 v6, 0x5800, v6
	global_load_dwordx2 v[12:13], v6, s[14:15]
	global_load_dwordx2 v[28:29], v6, s[16:17]
	v_add_u32_e32 v6, 0x5800, v6
	global_load_dwordx2 v[14:15], v6, s[14:15]
	global_load_dwordx2 v[30:31], v6, s[16:17]
	v_add_u32_e32 v6, 0x5800, v6
	global_load_dwordx2 v[16:17], v6, s[14:15]
	global_load_dwordx2 v[32:33], v6, s[16:17]
	v_add_u32_e32 v6, 0x5800, v6
	global_load_dwordx2 v[18:19], v6, s[14:15]
	global_load_dwordx2 v[34:35], v6, s[16:17]
	v_add_u32_e32 v6, 0x5800, v6
	global_load_dwordx2 v[20:21], v6, s[14:15]
	global_load_dwordx2 v[36:37], v6, s[16:17]
	v_add_u32_e32 v6, 0x5800, v6
	global_load_dwordx2 v[22:23], v6, s[14:15]
	global_load_dwordx2 v[38:39], v6, s[16:17]
	v_mov_b32_e32 v4, v117
	global_store_dwordx2 v4, v[216:217], s[18:19]
	v_add_u32_e32 v4, 0x2c00, v4
	global_store_dwordx2 v4, v[216:217], s[18:19]
	v_add_u32_e32 v4, 0x2c00, v4
	global_store_dwordx2 v4, v[216:217], s[18:19]
	v_add_u32_e32 v4, 0x2c00, v4
	global_store_dwordx2 v4, v[216:217], s[18:19]
	v_add_u32_e32 v4, 0x2c00, v4
	global_store_dwordx2 v4, v[216:217], s[18:19]
	v_add_u32_e32 v4, 0x2c00, v4
	global_store_dwordx2 v4, v[216:217], s[18:19]
	v_add_u32_e32 v4, 0x2c00, v4
	global_store_dwordx2 v4, v[216:217], s[18:19]
	v_add_u32_e32 v4, 0x2c00, v4
	global_store_dwordx2 v4, v[216:217], s[18:19]
	s_waitcnt vmcnt(24)
	s_mov_b64 s[6:7], exec
.Lcv_loop:
	v_and_b32_e32 v5, 0x1ff, v111
	v_cmp_eq_u32_e32 vcc, 0, v5
	s_nop 1
	v_cndmask_b32_e32 v118, v52, v216, vcc
	v_cndmask_b32_e32 v119, v53, v216, vcc
	v_cndmask_b32_e32 v122, v68, v216, vcc
	v_cndmask_b32_e32 v123, v69, v216, vcc
	v_cndmask_b32_e32 v120, v54, v216, vcc
	v_cndmask_b32_e32 v121, v55, v216, vcc
	v_cndmask_b32_e32 v124, v70, v216, vcc
	v_cndmask_b32_e32 v125, v71, v216, vcc
	v_add_u32_e32 v116, 1, v111
	v_cmp_lt_u32_e32 vcc, v116, v112
	s_and_b64 s[28:29], vcc, exec
	s_nop 0
	v_cndmask_b32_e32 v108, v111, v116, vcc
	v_lshlrev_b32_e32 v5, 3, v108
	v_mul_u32_u24_e32 v6, 0x5800, v5
	v_add_u32_e32 v6, v6, v113
	v_mul_u32_u24_e32 v7, 0x2c00, v5
	v_add_u32_e32 v7, v7, v113
	v_mov_b32_e32 v109, v7
	global_load_dwordx2 v[40:41], v6, s[14:15]
	global_load_dwordx2 v[56:57], v6, s[16:17]
	v_add_u32_e32 v6, 0x5800, v6
	global_load_dwordx2 v[42:43], v6, s[14:15]
	global_load_dwordx2 v[58:59], v6, s[16:17]
	v_add_u32_e32 v6, 0x5800, v6
	global_load_dwordx2 v[44:45], v6, s[14:15]
	global_load_dwordx2 v[60:61], v6, s[16:17]
	v_add_u32_e32 v6, 0x5800, v6
	global_load_dwordx2 v[46:47], v6, s[14:15]
	global_load_dwordx2 v[62:63], v6, s[16:17]
	v_add_u32_e32 v6, 0x5800, v6
	global_load_dwordx2 v[48:49], v6, s[14:15]
	global_load_dwordx2 v[64:65], v6, s[16:17]
	v_add_u32_e32 v6, 0x5800, v6
	global_load_dwordx2 v[50:51], v6, s[14:15]
	global_load_dwordx2 v[66:67], v6, s[16:17]
	v_add_u32_e32 v6, 0x5800, v6
	global_load_dwordx2 v[52:53], v6, s[14:15]
	global_load_dwordx2 v[68:69], v6, s[16:17]
	v_add_u32_e32 v6, 0x5800, v6
	global_load_dwordx2 v[54:55], v6, s[14:15]
	global_load_dwordx2 v[70:71], v6, s[16:17]
	s_waitcnt vmcnt(24)
	v_lshlrev_b32_e32 v160, 16, v118
	v_and_b32_e32 v161, 0xffff0000, v118
	v_lshlrev_b32_e32 v162, 16, v119
	v_and_b32_e32 v163, 0xffff0000, v119
	v_lshlrev_b32_e32 v172, 16, v122
	v_and_b32_e32 v173, 0xffff0000, v122
	v_lshlrev_b32_e32 v174, 16, v123
	v_and_b32_e32 v175, 0xffff0000, v123
	v_lshlrev_b32_e32 v164, 16, v120
	v_and_b32_e32 v165, 0xffff0000, v120
	v_lshlrev_b32_e32 v166, 16, v121
	v_and_b32_e32 v167, 0xffff0000, v121
	v_lshlrev_b32_e32 v176, 16, v124
	v_and_b32_e32 v177, 0xffff0000, v124
	v_lshlrev_b32_e32 v178, 16, v125
	v_and_b32_e32 v179, 0xffff0000, v125
	v_lshlrev_b32_e32 v168, 16, v8
	v_and_b32_e32 v169, 0xffff0000, v8
	v_lshlrev_b32_e32 v170, 16, v9
	v_and_b32_e32 v171, 0xffff0000, v9
	v_lshlrev_b32_e32 v180, 16, v24
	v_and_b32_e32 v181, 0xffff0000, v24
	v_lshlrev_b32_e32 v182, 16, v25
	v_and_b32_e32 v183, 0xffff0000, v25
	v_pk_mul_f32 v[184:185], v[72:73], v[164:165]
	v_pk_mul_f32 v[188:189], v[88:89], v[176:177]
	v_pk_mul_f32 v[186:187], v[74:75], v[166:167]
	v_pk_mul_f32 v[190:191], v[90:91], v[178:179]
	v_pk_fma_f32 v[184:185], v[76:77], v[160:161], v[184:185]
	v_pk_fma_f32 v[188:189], v[92:93], v[172:173], v[188:189]
	v_pk_fma_f32 v[186:187], v[78:79], v[162:163], v[186:187]
	v_pk_fma_f32 v[190:191], v[94:95], v[174:175], v[190:191]
	v_pk_fma_f32 v[184:185], v[80:81], v[168:169], v[184:185]
	v_pk_fma_f32 v[188:189], v[96:97], v[180:181], v[188:189]
	v_pk_fma_f32 v[186:187], v[82:83], v[170:171], v[186:187]
	v_pk_fma_f32 v[190:191], v[98:99], v[182:183], v[190:191]
	v_pk_add_f32 v[184:185], v[184:185], v[84:85]
	v_pk_add_f32 v[188:189], v[188:189], v[100:101]
	v_pk_add_f32 v[186:187], v[186:187], v[86:87]
	v_pk_add_f32 v[190:191], v[190:191], v[102:103]
	v_mul_f32_e32 v192, 0xbfb8aa3b, v188
	v_mul_f32_e32 v193, 0xbfb8aa3b, v189
	v_mul_f32_e32 v194, 0xbfb8aa3b, v190
	v_mul_f32_e32 v195, 0xbfb8aa3b, v191
	v_exp_f32_e32 v192, v192
	v_exp_f32_e32 v193, v193
	v_exp_f32_e32 v194, v194
	v_exp_f32_e32 v195, v195
	s_nop 0
	v_pk_add_f32 v[192:193], v[192:193], 1.0 op_sel_hi:[1,0]
	v_pk_add_f32 v[194:195], v[194:195], 1.0 op_sel_hi:[1,0]
	v_div_scale_f32 v224, s[8:9], v192, v192, 1.0
	v_div_scale_f32 v229, s[8:9], v193, v193, 1.0
	v_div_scale_f32 v234, s[8:9], v194, v194, 1.0
	v_div_scale_f32 v239, s[8:9], v195, v195, 1.0
	v_div_scale_f32 v225, s[20:21], 1.0, v192, 1.0
	v_div_scale_f32 v230, s[22:23], 1.0, v193, 1.0
	v_div_scale_f32 v235, s[24:25], 1.0, v194, 1.0
	v_div_scale_f32 v240, s[26:27], 1.0, v195, 1.0
	v_rcp_f32_e32 v226, v224
	v_rcp_f32_e32 v231, v229
	v_rcp_f32_e32 v236, v234
	v_rcp_f32_e32 v241, v239
	v_fma_f32 v228, -v224, v226, 1.0
	v_fma_f32 v233, -v229, v231, 1.0
	v_fma_f32 v238, -v234, v236, 1.0
	v_fma_f32 v243, -v239, v241, 1.0
	v_fmac_f32_e32 v226, v228, v226
	v_fmac_f32_e32 v231, v233, v231
	v_fmac_f32_e32 v236, v238, v236
	v_fmac_f32_e32 v241, v243, v241
	v_mul_f32_e32 v227, v225, v226
	v_mul_f32_e32 v232, v230, v231
	v_mul_f32_e32 v237, v235, v236
	v_mul_f32_e32 v242, v240, v241
	v_fma_f32 v228, -v224, v227, v225
	v_fma_f32 v233, -v229, v232, v230
	v_fma_f32 v238, -v234, v237, v235
	v_fma_f32 v243, -v239, v242, v240
	v_fmac_f32_e32 v227, v228, v226
	v_fmac_f32_e32 v232, v233, v231
	v_fmac_f32_e32 v237, v238, v236
	v_fmac_f32_e32 v242, v243, v241
	v_fma_f32 v228, -v224, v227, v225
	v_fma_f32 v233, -v229, v232, v230
	v_fma_f32 v238, -v234, v237, v235
	v_fma_f32 v243, -v239, v242, v240
	s_mov_b64 vcc, s[20:21]
	s_nop 0
	v_div_fmas_f32 v228, v228, v226, v227
	s_mov_b64 vcc, s[22:23]
	s_nop 0
	v_div_fmas_f32 v233, v233, v231, v232
	s_mov_b64 vcc, s[24:25]
	s_nop 0
	v_div_fmas_f32 v238, v238, v236, v237
	s_mov_b64 vcc, s[26:27]
	s_nop 0
	v_div_fmas_f32 v243, v243, v241, v242
	v_div_fixup_f32 v196, v228, v192, 1.0
	v_div_fixup_f32 v197, v233, v193, 1.0
	v_div_fixup_f32 v198, v238, v194, 1.0
	v_div_fixup_f32 v199, v243, v195, 1.0
	v_pk_mul_f32 v[196:197], v[188:189], v[196:197]
	v_pk_mul_f32 v[198:199], v[190:191], v[198:199]
	v_pk_mul_f32 v[196:197], v[184:185], v[196:197]
	v_pk_mul_f32 v[198:199], v[186:187], v[198:199]
	v_cvt_pk_bf16_f32 v206, v196, v197
	v_cvt_pk_bf16_f32 v207, v198, v199
	global_store_dwordx2 v117, v[206:207], s[18:19]
	v_lshlrev_b32_e32 v160, 16, v10
	v_and_b32_e32 v161, 0xffff0000, v10
	v_lshlrev_b32_e32 v162, 16, v11
	v_and_b32_e32 v163, 0xffff0000, v11
	v_lshlrev_b32_e32 v172, 16, v26
	v_and_b32_e32 v173, 0xffff0000, v26
	v_lshlrev_b32_e32 v174, 16, v27
	v_and_b32_e32 v175, 0xffff0000, v27
	v_pk_mul_f32 v[184:185], v[72:73], v[168:169]
	v_pk_mul_f32 v[188:189], v[88:89], v[180:181]
	v_pk_mul_f32 v[186:187], v[74:75], v[170:171]
	v_pk_mul_f32 v[190:191], v[90:91], v[182:183]
	v_pk_fma_f32 v[184:185], v[76:77], v[164:165], v[184:185]
	v_pk_fma_f32 v[188:189], v[92:93], v[176:177], v[188:189]
	v_pk_fma_f32 v[186:187], v[78:79], v[166:167], v[186:187]
	v_pk_fma_f32 v[190:191], v[94:95], v[178:179], v[190:191]
	v_pk_fma_f32 v[184:185], v[80:81], v[160:161], v[184:185]
	v_pk_fma_f32 v[188:189], v[96:97], v[172:173], v[188:189]
	v_pk_fma_f32 v[186:187], v[82:83], v[162:163], v[186:187]
	v_pk_fma_f32 v[190:191], v[98:99], v[174:175], v[190:191]
	v_pk_add_f32 v[184:185], v[184:185], v[84:85]
	v_pk_add_f32 v[188:189], v[188:189], v[100:101]
	v_pk_add_f32 v[186:187], v[186:187], v[86:87]
	v_pk_add_f32 v[190:191], v[190:191], v[102:103]
	v_mul_f32_e32 v192, 0xbfb8aa3b, v188
	v_mul_f32_e32 v193, 0xbfb8aa3b, v189
	v_mul_f32_e32 v194, 0xbfb8aa3b, v190
	v_mul_f32_e32 v195, 0xbfb8aa3b, v191
	v_exp_f32_e32 v192, v192
	v_exp_f32_e32 v193, v193
	v_exp_f32_e32 v194, v194
	v_exp_f32_e32 v195, v195
	s_nop 0
	v_pk_add_f32 v[192:193], v[192:193], 1.0 op_sel_hi:[1,0]
	v_pk_add_f32 v[194:195], v[194:195], 1.0 op_sel_hi:[1,0]
	v_div_scale_f32 v224, s[8:9], v192, v192, 1.0
	v_div_scale_f32 v229, s[8:9], v193, v193, 1.0
	v_div_scale_f32 v234, s[8:9], v194, v194, 1.0
	v_div_scale_f32 v239, s[8:9], v195, v195, 1.0
	v_div_scale_f32 v225, s[20:21], 1.0, v192, 1.0
	v_div_scale_f32 v230, s[22:23], 1.0, v193, 1.0
	v_div_scale_f32 v235, s[24:25], 1.0, v194, 1.0
	v_div_scale_f32 v240, s[26:27], 1.0, v195, 1.0
	v_rcp_f32_e32 v226, v224
	v_rcp_f32_e32 v231, v229
	v_rcp_f32_e32 v236, v234
	v_rcp_f32_e32 v241, v239
	v_fma_f32 v228, -v224, v226, 1.0
	v_fma_f32 v233, -v229, v231, 1.0
	v_fma_f32 v238, -v234, v236, 1.0
	v_fma_f32 v243, -v239, v241, 1.0
	v_fmac_f32_e32 v226, v228, v226
	v_fmac_f32_e32 v231, v233, v231
	v_fmac_f32_e32 v236, v238, v236
	v_fmac_f32_e32 v241, v243, v241
	v_mul_f32_e32 v227, v225, v226
	v_mul_f32_e32 v232, v230, v231
	v_mul_f32_e32 v237, v235, v236
	v_mul_f32_e32 v242, v240, v241
	v_fma_f32 v228, -v224, v227, v225
	v_fma_f32 v233, -v229, v232, v230
	v_fma_f32 v238, -v234, v237, v235
	v_fma_f32 v243, -v239, v242, v240
	v_fmac_f32_e32 v227, v228, v226
	v_fmac_f32_e32 v232, v233, v231
	v_fmac_f32_e32 v237, v238, v236
	v_fmac_f32_e32 v242, v243, v241
	v_fma_f32 v228, -v224, v227, v225
	v_fma_f32 v233, -v229, v232, v230
	v_fma_f32 v238, -v234, v237, v235
	v_fma_f32 v243, -v239, v242, v240
	s_mov_b64 vcc, s[20:21]
	s_nop 0
	v_div_fmas_f32 v228, v228, v226, v227
	s_mov_b64 vcc, s[22:23]
	s_nop 0
	v_div_fmas_f32 v233, v233, v231, v232
	s_mov_b64 vcc, s[24:25]
	s_nop 0
	v_div_fmas_f32 v238, v238, v236, v237
	s_mov_b64 vcc, s[26:27]
	s_nop 0
	v_div_fmas_f32 v243, v243, v241, v242
	v_div_fixup_f32 v196, v228, v192, 1.0
	v_div_fixup_f32 v197, v233, v193, 1.0
	v_div_fixup_f32 v198, v238, v194, 1.0
	v_div_fixup_f32 v199, v243, v195, 1.0
	v_pk_mul_f32 v[196:197], v[188:189], v[196:197]
	v_pk_mul_f32 v[198:199], v[190:191], v[198:199]
	v_pk_mul_f32 v[196:197], v[184:185], v[196:197]
	v_pk_mul_f32 v[198:199], v[186:187], v[198:199]
	v_cvt_pk_bf16_f32 v208, v196, v197
	v_cvt_pk_bf16_f32 v209, v198, v199
	v_add_u32_e32 v117, 0x2c00, v117
	global_store_dwordx2 v117, v[208:209], s[18:19]
	v_lshlrev_b32_e32 v164, 16, v12
	v_and_b32_e32 v165, 0xffff0000, v12
	v_lshlrev_b32_e32 v166, 16, v13
	v_and_b32_e32 v167, 0xffff0000, v13
	v_lshlrev_b32_e32 v176, 16, v28
	v_and_b32_e32 v177, 0xffff0000, v28
	v_lshlrev_b32_e32 v178, 16, v29
	v_and_b32_e32 v179, 0xffff0000, v29
	v_pk_mul_f32 v[184:185], v[72:73], v[160:161]
	v_pk_mul_f32 v[188:189], v[88:89], v[172:173]
	v_pk_mul_f32 v[186:187], v[74:75], v[162:163]
	v_pk_mul_f32 v[190:191], v[90:91], v[174:175]
	v_pk_fma_f32 v[184:185], v[76:77], v[168:169], v[184:185]
	v_pk_fma_f32 v[188:189], v[92:93], v[180:181], v[188:189]
	v_pk_fma_f32 v[186:187], v[78:79], v[170:171], v[186:187]
	v_pk_fma_f32 v[190:191], v[94:95], v[182:183], v[190:191]
	v_pk_fma_f32 v[184:185], v[80:81], v[164:165], v[184:185]
	v_pk_fma_f32 v[188:189], v[96:97], v[176:177], v[188:189]
	v_pk_fma_f32 v[186:187], v[82:83], v[166:167], v[186:187]
	v_pk_fma_f32 v[190:191], v[98:99], v[178:179], v[190:191]
	v_pk_add_f32 v[184:185], v[184:185], v[84:85]
	v_pk_add_f32 v[188:189], v[188:189], v[100:101]
	v_pk_add_f32 v[186:187], v[186:187], v[86:87]
	v_pk_add_f32 v[190:191], v[190:191], v[102:103]
	v_mul_f32_e32 v192, 0xbfb8aa3b, v188
	v_mul_f32_e32 v193, 0xbfb8aa3b, v189
	v_mul_f32_e32 v194, 0xbfb8aa3b, v190
	v_mul_f32_e32 v195, 0xbfb8aa3b, v191
	v_exp_f32_e32 v192, v192
	v_exp_f32_e32 v193, v193
	v_exp_f32_e32 v194, v194
	v_exp_f32_e32 v195, v195
	s_nop 0
	v_pk_add_f32 v[192:193], v[192:193], 1.0 op_sel_hi:[1,0]
	v_pk_add_f32 v[194:195], v[194:195], 1.0 op_sel_hi:[1,0]
	v_div_scale_f32 v224, s[8:9], v192, v192, 1.0
	v_div_scale_f32 v229, s[8:9], v193, v193, 1.0
	v_div_scale_f32 v234, s[8:9], v194, v194, 1.0
	v_div_scale_f32 v239, s[8:9], v195, v195, 1.0
	v_div_scale_f32 v225, s[20:21], 1.0, v192, 1.0
	v_div_scale_f32 v230, s[22:23], 1.0, v193, 1.0
	v_div_scale_f32 v235, s[24:25], 1.0, v194, 1.0
	v_div_scale_f32 v240, s[26:27], 1.0, v195, 1.0
	v_rcp_f32_e32 v226, v224
	v_rcp_f32_e32 v231, v229
	v_rcp_f32_e32 v236, v234
	v_rcp_f32_e32 v241, v239
	v_fma_f32 v228, -v224, v226, 1.0
	v_fma_f32 v233, -v229, v231, 1.0
	v_fma_f32 v238, -v234, v236, 1.0
	v_fma_f32 v243, -v239, v241, 1.0
	v_fmac_f32_e32 v226, v228, v226
	v_fmac_f32_e32 v231, v233, v231
	v_fmac_f32_e32 v236, v238, v236
	v_fmac_f32_e32 v241, v243, v241
	v_mul_f32_e32 v227, v225, v226
	v_mul_f32_e32 v232, v230, v231
	v_mul_f32_e32 v237, v235, v236
	v_mul_f32_e32 v242, v240, v241
	v_fma_f32 v228, -v224, v227, v225
	v_fma_f32 v233, -v229, v232, v230
	v_fma_f32 v238, -v234, v237, v235
	v_fma_f32 v243, -v239, v242, v240
	v_fmac_f32_e32 v227, v228, v226
	v_fmac_f32_e32 v232, v233, v231
	v_fmac_f32_e32 v237, v238, v236
	v_fmac_f32_e32 v242, v243, v241
	v_fma_f32 v228, -v224, v227, v225
	v_fma_f32 v233, -v229, v232, v230
	v_fma_f32 v238, -v234, v237, v235
	v_fma_f32 v243, -v239, v242, v240
	s_mov_b64 vcc, s[20:21]
	s_nop 0
	v_div_fmas_f32 v228, v228, v226, v227
	s_mov_b64 vcc, s[22:23]
	s_nop 0
	v_div_fmas_f32 v233, v233, v231, v232
	s_mov_b64 vcc, s[24:25]
	s_nop 0
	v_div_fmas_f32 v238, v238, v236, v237
	s_mov_b64 vcc, s[26:27]
	s_nop 0
	v_div_fmas_f32 v243, v243, v241, v242
	v_div_fixup_f32 v196, v228, v192, 1.0
	v_div_fixup_f32 v197, v233, v193, 1.0
	v_div_fixup_f32 v198, v238, v194, 1.0
	v_div_fixup_f32 v199, v243, v195, 1.0
	v_pk_mul_f32 v[196:197], v[188:189], v[196:197]
	v_pk_mul_f32 v[198:199], v[190:191], v[198:199]
	v_pk_mul_f32 v[196:197], v[184:185], v[196:197]
	v_pk_mul_f32 v[198:199], v[186:187], v[198:199]
	v_cvt_pk_bf16_f32 v206, v196, v197
	v_cvt_pk_bf16_f32 v207, v198, v199
	v_add_u32_e32 v117, 0x2c00, v117
	global_store_dwordx2 v117, v[206:207], s[18:19]
	v_lshlrev_b32_e32 v168, 16, v14
	v_and_b32_e32 v169, 0xffff0000, v14
	v_lshlrev_b32_e32 v170, 16, v15
	v_and_b32_e32 v171, 0xffff0000, v15
	v_lshlrev_b32_e32 v180, 16, v30
	v_and_b32_e32 v181, 0xffff0000, v30
	v_lshlrev_b32_e32 v182, 16, v31
	v_and_b32_e32 v183, 0xffff0000, v31
	v_pk_mul_f32 v[184:185], v[72:73], v[164:165]
	v_pk_mul_f32 v[188:189], v[88:89], v[176:177]
	v_pk_mul_f32 v[186:187], v[74:75], v[166:167]
	v_pk_mul_f32 v[190:191], v[90:91], v[178:179]
	v_pk_fma_f32 v[184:185], v[76:77], v[160:161], v[184:185]
	v_pk_fma_f32 v[188:189], v[92:93], v[172:173], v[188:189]
	v_pk_fma_f32 v[186:187], v[78:79], v[162:163], v[186:187]
	v_pk_fma_f32 v[190:191], v[94:95], v[174:175], v[190:191]
	v_pk_fma_f32 v[184:185], v[80:81], v[168:169], v[184:185]
	v_pk_fma_f32 v[188:189], v[96:97], v[180:181], v[188:189]
	v_pk_fma_f32 v[186:187], v[82:83], v[170:171], v[186:187]
	v_pk_fma_f32 v[190:191], v[98:99], v[182:183], v[190:191]
	v_pk_add_f32 v[184:185], v[184:185], v[84:85]
	v_pk_add_f32 v[188:189], v[188:189], v[100:101]
	v_pk_add_f32 v[186:187], v[186:187], v[86:87]
	v_pk_add_f32 v[190:191], v[190:191], v[102:103]
	v_mul_f32_e32 v192, 0xbfb8aa3b, v188
	v_mul_f32_e32 v193, 0xbfb8aa3b, v189
	v_mul_f32_e32 v194, 0xbfb8aa3b, v190
	v_mul_f32_e32 v195, 0xbfb8aa3b, v191
	v_exp_f32_e32 v192, v192
	v_exp_f32_e32 v193, v193
	v_exp_f32_e32 v194, v194
	v_exp_f32_e32 v195, v195
	s_nop 0
	v_pk_add_f32 v[192:193], v[192:193], 1.0 op_sel_hi:[1,0]
	v_pk_add_f32 v[194:195], v[194:195], 1.0 op_sel_hi:[1,0]
	v_div_scale_f32 v224, s[8:9], v192, v192, 1.0
	v_div_scale_f32 v229, s[8:9], v193, v193, 1.0
	v_div_scale_f32 v234, s[8:9], v194, v194, 1.0
	v_div_scale_f32 v239, s[8:9], v195, v195, 1.0
	v_div_scale_f32 v225, s[20:21], 1.0, v192, 1.0
	v_div_scale_f32 v230, s[22:23], 1.0, v193, 1.0
	v_div_scale_f32 v235, s[24:25], 1.0, v194, 1.0
	v_div_scale_f32 v240, s[26:27], 1.0, v195, 1.0
	v_rcp_f32_e32 v226, v224
	v_rcp_f32_e32 v231, v229
	v_rcp_f32_e32 v236, v234
	v_rcp_f32_e32 v241, v239
	v_fma_f32 v228, -v224, v226, 1.0
	v_fma_f32 v233, -v229, v231, 1.0
	v_fma_f32 v238, -v234, v236, 1.0
	v_fma_f32 v243, -v239, v241, 1.0
	v_fmac_f32_e32 v226, v228, v226
	v_fmac_f32_e32 v231, v233, v231
	v_fmac_f32_e32 v236, v238, v236
	v_fmac_f32_e32 v241, v243, v241
	v_mul_f32_e32 v227, v225, v226
	v_mul_f32_e32 v232, v230, v231
	v_mul_f32_e32 v237, v235, v236
	v_mul_f32_e32 v242, v240, v241
	v_fma_f32 v228, -v224, v227, v225
	v_fma_f32 v233, -v229, v232, v230
	v_fma_f32 v238, -v234, v237, v235
	v_fma_f32 v243, -v239, v242, v240
	v_fmac_f32_e32 v227, v228, v226
	v_fmac_f32_e32 v232, v233, v231
	v_fmac_f32_e32 v237, v238, v236
	v_fmac_f32_e32 v242, v243, v241
	v_fma_f32 v228, -v224, v227, v225
	v_fma_f32 v233, -v229, v232, v230
	v_fma_f32 v238, -v234, v237, v235
	v_fma_f32 v243, -v239, v242, v240
	s_mov_b64 vcc, s[20:21]
	s_nop 0
	v_div_fmas_f32 v228, v228, v226, v227
	s_mov_b64 vcc, s[22:23]
	s_nop 0
	v_div_fmas_f32 v233, v233, v231, v232
	s_mov_b64 vcc, s[24:25]
	s_nop 0
	v_div_fmas_f32 v238, v238, v236, v237
	s_mov_b64 vcc, s[26:27]
	s_nop 0
	v_div_fmas_f32 v243, v243, v241, v242
	v_div_fixup_f32 v196, v228, v192, 1.0
	v_div_fixup_f32 v197, v233, v193, 1.0
	v_div_fixup_f32 v198, v238, v194, 1.0
	v_div_fixup_f32 v199, v243, v195, 1.0
	v_pk_mul_f32 v[196:197], v[188:189], v[196:197]
	v_pk_mul_f32 v[198:199], v[190:191], v[198:199]
	v_pk_mul_f32 v[196:197], v[184:185], v[196:197]
	v_pk_mul_f32 v[198:199], v[186:187], v[198:199]
	v_cvt_pk_bf16_f32 v208, v196, v197
	v_cvt_pk_bf16_f32 v209, v198, v199
	v_add_u32_e32 v117, 0x2c00, v117
	global_store_dwordx2 v117, v[208:209], s[18:19]
	v_lshlrev_b32_e32 v160, 16, v16
	v_and_b32_e32 v161, 0xffff0000, v16
	v_lshlrev_b32_e32 v162, 16, v17
	v_and_b32_e32 v163, 0xffff0000, v17
	v_lshlrev_b32_e32 v172, 16, v32
	v_and_b32_e32 v173, 0xffff0000, v32
	v_lshlrev_b32_e32 v174, 16, v33
	v_and_b32_e32 v175, 0xffff0000, v33
	v_pk_mul_f32 v[184:185], v[72:73], v[168:169]
	v_pk_mul_f32 v[188:189], v[88:89], v[180:181]
	v_pk_mul_f32 v[186:187], v[74:75], v[170:171]
	v_pk_mul_f32 v[190:191], v[90:91], v[182:183]
	v_pk_fma_f32 v[184:185], v[76:77], v[164:165], v[184:185]
	v_pk_fma_f32 v[188:189], v[92:93], v[176:177], v[188:189]
	v_pk_fma_f32 v[186:187], v[78:79], v[166:167], v[186:187]
	v_pk_fma_f32 v[190:191], v[94:95], v[178:179], v[190:191]
	v_pk_fma_f32 v[184:185], v[80:81], v[160:161], v[184:185]
	v_pk_fma_f32 v[188:189], v[96:97], v[172:173], v[188:189]
	v_pk_fma_f32 v[186:187], v[82:83], v[162:163], v[186:187]
	v_pk_fma_f32 v[190:191], v[98:99], v[174:175], v[190:191]
	v_pk_add_f32 v[184:185], v[184:185], v[84:85]
	v_pk_add_f32 v[188:189], v[188:189], v[100:101]
	v_pk_add_f32 v[186:187], v[186:187], v[86:87]
	v_pk_add_f32 v[190:191], v[190:191], v[102:103]
	v_mul_f32_e32 v192, 0xbfb8aa3b, v188
	v_mul_f32_e32 v193, 0xbfb8aa3b, v189
	v_mul_f32_e32 v194, 0xbfb8aa3b, v190
	v_mul_f32_e32 v195, 0xbfb8aa3b, v191
	v_exp_f32_e32 v192, v192
	v_exp_f32_e32 v193, v193
	v_exp_f32_e32 v194, v194
	v_exp_f32_e32 v195, v195
	s_nop 0
	v_pk_add_f32 v[192:193], v[192:193], 1.0 op_sel_hi:[1,0]
	v_pk_add_f32 v[194:195], v[194:195], 1.0 op_sel_hi:[1,0]
	v_div_scale_f32 v224, s[8:9], v192, v192, 1.0
	v_div_scale_f32 v229, s[8:9], v193, v193, 1.0
	v_div_scale_f32 v234, s[8:9], v194, v194, 1.0
	v_div_scale_f32 v239, s[8:9], v195, v195, 1.0
	v_div_scale_f32 v225, s[20:21], 1.0, v192, 1.0
	v_div_scale_f32 v230, s[22:23], 1.0, v193, 1.0
	v_div_scale_f32 v235, s[24:25], 1.0, v194, 1.0
	v_div_scale_f32 v240, s[26:27], 1.0, v195, 1.0
	v_rcp_f32_e32 v226, v224
	v_rcp_f32_e32 v231, v229
	v_rcp_f32_e32 v236, v234
	v_rcp_f32_e32 v241, v239
	v_fma_f32 v228, -v224, v226, 1.0
	v_fma_f32 v233, -v229, v231, 1.0
	v_fma_f32 v238, -v234, v236, 1.0
	v_fma_f32 v243, -v239, v241, 1.0
	v_fmac_f32_e32 v226, v228, v226
	v_fmac_f32_e32 v231, v233, v231
	v_fmac_f32_e32 v236, v238, v236
	v_fmac_f32_e32 v241, v243, v241
	v_mul_f32_e32 v227, v225, v226
	v_mul_f32_e32 v232, v230, v231
	v_mul_f32_e32 v237, v235, v236
	v_mul_f32_e32 v242, v240, v241
	v_fma_f32 v228, -v224, v227, v225
	v_fma_f32 v233, -v229, v232, v230
	v_fma_f32 v238, -v234, v237, v235
	v_fma_f32 v243, -v239, v242, v240
	v_fmac_f32_e32 v227, v228, v226
	v_fmac_f32_e32 v232, v233, v231
	v_fmac_f32_e32 v237, v238, v236
	v_fmac_f32_e32 v242, v243, v241
	v_fma_f32 v228, -v224, v227, v225
	v_fma_f32 v233, -v229, v232, v230
	v_fma_f32 v238, -v234, v237, v235
	v_fma_f32 v243, -v239, v242, v240
	s_mov_b64 vcc, s[20:21]
	s_nop 0
	v_div_fmas_f32 v228, v228, v226, v227
	s_mov_b64 vcc, s[22:23]
	s_nop 0
	v_div_fmas_f32 v233, v233, v231, v232
	s_mov_b64 vcc, s[24:25]
	s_nop 0
	v_div_fmas_f32 v238, v238, v236, v237
	s_mov_b64 vcc, s[26:27]
	s_nop 0
	v_div_fmas_f32 v243, v243, v241, v242
	v_div_fixup_f32 v196, v228, v192, 1.0
	v_div_fixup_f32 v197, v233, v193, 1.0
	v_div_fixup_f32 v198, v238, v194, 1.0
	v_div_fixup_f32 v199, v243, v195, 1.0
	v_pk_mul_f32 v[196:197], v[188:189], v[196:197]
	v_pk_mul_f32 v[198:199], v[190:191], v[198:199]
	v_pk_mul_f32 v[196:197], v[184:185], v[196:197]
	v_pk_mul_f32 v[198:199], v[186:187], v[198:199]
	v_cvt_pk_bf16_f32 v206, v196, v197
	v_cvt_pk_bf16_f32 v207, v198, v199
	v_add_u32_e32 v117, 0x2c00, v117
	global_store_dwordx2 v117, v[206:207], s[18:19]
	v_lshlrev_b32_e32 v164, 16, v18
	v_and_b32_e32 v165, 0xffff0000, v18
	v_lshlrev_b32_e32 v166, 16, v19
	v_and_b32_e32 v167, 0xffff0000, v19
	v_lshlrev_b32_e32 v176, 16, v34
	v_and_b32_e32 v177, 0xffff0000, v34
	v_lshlrev_b32_e32 v178, 16, v35
	v_and_b32_e32 v179, 0xffff0000, v35
	v_pk_mul_f32 v[184:185], v[72:73], v[160:161]
	v_pk_mul_f32 v[188:189], v[88:89], v[172:173]
	v_pk_mul_f32 v[186:187], v[74:75], v[162:163]
	v_pk_mul_f32 v[190:191], v[90:91], v[174:175]
	v_pk_fma_f32 v[184:185], v[76:77], v[168:169], v[184:185]
	v_pk_fma_f32 v[188:189], v[92:93], v[180:181], v[188:189]
	v_pk_fma_f32 v[186:187], v[78:79], v[170:171], v[186:187]
	v_pk_fma_f32 v[190:191], v[94:95], v[182:183], v[190:191]
	v_pk_fma_f32 v[184:185], v[80:81], v[164:165], v[184:185]
	v_pk_fma_f32 v[188:189], v[96:97], v[176:177], v[188:189]
	v_pk_fma_f32 v[186:187], v[82:83], v[166:167], v[186:187]
	v_pk_fma_f32 v[190:191], v[98:99], v[178:179], v[190:191]
	v_pk_add_f32 v[184:185], v[184:185], v[84:85]
	v_pk_add_f32 v[188:189], v[188:189], v[100:101]
	v_pk_add_f32 v[186:187], v[186:187], v[86:87]
	v_pk_add_f32 v[190:191], v[190:191], v[102:103]
	v_mul_f32_e32 v192, 0xbfb8aa3b, v188
	v_mul_f32_e32 v193, 0xbfb8aa3b, v189
	v_mul_f32_e32 v194, 0xbfb8aa3b, v190
	v_mul_f32_e32 v195, 0xbfb8aa3b, v191
	v_exp_f32_e32 v192, v192
	v_exp_f32_e32 v193, v193
	v_exp_f32_e32 v194, v194
	v_exp_f32_e32 v195, v195
	s_nop 0
	v_pk_add_f32 v[192:193], v[192:193], 1.0 op_sel_hi:[1,0]
	v_pk_add_f32 v[194:195], v[194:195], 1.0 op_sel_hi:[1,0]
	v_div_scale_f32 v224, s[8:9], v192, v192, 1.0
	v_div_scale_f32 v229, s[8:9], v193, v193, 1.0
	v_div_scale_f32 v234, s[8:9], v194, v194, 1.0
	v_div_scale_f32 v239, s[8:9], v195, v195, 1.0
	v_div_scale_f32 v225, s[20:21], 1.0, v192, 1.0
	v_div_scale_f32 v230, s[22:23], 1.0, v193, 1.0
	v_div_scale_f32 v235, s[24:25], 1.0, v194, 1.0
	v_div_scale_f32 v240, s[26:27], 1.0, v195, 1.0
	v_rcp_f32_e32 v226, v224
	v_rcp_f32_e32 v231, v229
	v_rcp_f32_e32 v236, v234
	v_rcp_f32_e32 v241, v239
	v_fma_f32 v228, -v224, v226, 1.0
	v_fma_f32 v233, -v229, v231, 1.0
	v_fma_f32 v238, -v234, v236, 1.0
	v_fma_f32 v243, -v239, v241, 1.0
	v_fmac_f32_e32 v226, v228, v226
	v_fmac_f32_e32 v231, v233, v231
	v_fmac_f32_e32 v236, v238, v236
	v_fmac_f32_e32 v241, v243, v241
	v_mul_f32_e32 v227, v225, v226
	v_mul_f32_e32 v232, v230, v231
	v_mul_f32_e32 v237, v235, v236
	v_mul_f32_e32 v242, v240, v241
	v_fma_f32 v228, -v224, v227, v225
	v_fma_f32 v233, -v229, v232, v230
	v_fma_f32 v238, -v234, v237, v235
	v_fma_f32 v243, -v239, v242, v240
	v_fmac_f32_e32 v227, v228, v226
	v_fmac_f32_e32 v232, v233, v231
	v_fmac_f32_e32 v237, v238, v236
	v_fmac_f32_e32 v242, v243, v241
	v_fma_f32 v228, -v224, v227, v225
	v_fma_f32 v233, -v229, v232, v230
	v_fma_f32 v238, -v234, v237, v235
	v_fma_f32 v243, -v239, v242, v240
	s_mov_b64 vcc, s[20:21]
	s_nop 0
	v_div_fmas_f32 v228, v228, v226, v227
	s_mov_b64 vcc, s[22:23]
	s_nop 0
	v_div_fmas_f32 v233, v233, v231, v232
	s_mov_b64 vcc, s[24:25]
	s_nop 0
	v_div_fmas_f32 v238, v238, v236, v237
	s_mov_b64 vcc, s[26:27]
	s_nop 0
	v_div_fmas_f32 v243, v243, v241, v242
	v_div_fixup_f32 v196, v228, v192, 1.0
	v_div_fixup_f32 v197, v233, v193, 1.0
	v_div_fixup_f32 v198, v238, v194, 1.0
	v_div_fixup_f32 v199, v243, v195, 1.0
	v_pk_mul_f32 v[196:197], v[188:189], v[196:197]
	v_pk_mul_f32 v[198:199], v[190:191], v[198:199]
	v_pk_mul_f32 v[196:197], v[184:185], v[196:197]
	v_pk_mul_f32 v[198:199], v[186:187], v[198:199]
	v_cvt_pk_bf16_f32 v208, v196, v197
	v_cvt_pk_bf16_f32 v209, v198, v199
	v_add_u32_e32 v117, 0x2c00, v117
	global_store_dwordx2 v117, v[208:209], s[18:19]
	v_lshlrev_b32_e32 v168, 16, v20
	v_and_b32_e32 v169, 0xffff0000, v20
	v_lshlrev_b32_e32 v170, 16, v21
	v_and_b32_e32 v171, 0xffff0000, v21
	v_lshlrev_b32_e32 v180, 16, v36
	v_and_b32_e32 v181, 0xffff0000, v36
	v_lshlrev_b32_e32 v182, 16, v37
	v_and_b32_e32 v183, 0xffff0000, v37
	v_pk_mul_f32 v[184:185], v[72:73], v[164:165]
	v_pk_mul_f32 v[188:189], v[88:89], v[176:177]
	v_pk_mul_f32 v[186:187], v[74:75], v[166:167]
	v_pk_mul_f32 v[190:191], v[90:91], v[178:179]
	v_pk_fma_f32 v[184:185], v[76:77], v[160:161], v[184:185]
	v_pk_fma_f32 v[188:189], v[92:93], v[172:173], v[188:189]
	v_pk_fma_f32 v[186:187], v[78:79], v[162:163], v[186:187]
	v_pk_fma_f32 v[190:191], v[94:95], v[174:175], v[190:191]
	v_pk_fma_f32 v[184:185], v[80:81], v[168:169], v[184:185]
	v_pk_fma_f32 v[188:189], v[96:97], v[180:181], v[188:189]
	v_pk_fma_f32 v[186:187], v[82:83], v[170:171], v[186:187]
	v_pk_fma_f32 v[190:191], v[98:99], v[182:183], v[190:191]
	v_pk_add_f32 v[184:185], v[184:185], v[84:85]
	v_pk_add_f32 v[188:189], v[188:189], v[100:101]
	v_pk_add_f32 v[186:187], v[186:187], v[86:87]
	v_pk_add_f32 v[190:191], v[190:191], v[102:103]
	v_mul_f32_e32 v192, 0xbfb8aa3b, v188
	v_mul_f32_e32 v193, 0xbfb8aa3b, v189
	v_mul_f32_e32 v194, 0xbfb8aa3b, v190
	v_mul_f32_e32 v195, 0xbfb8aa3b, v191
	v_exp_f32_e32 v192, v192
	v_exp_f32_e32 v193, v193
	v_exp_f32_e32 v194, v194
	v_exp_f32_e32 v195, v195
	s_nop 0
	v_pk_add_f32 v[192:193], v[192:193], 1.0 op_sel_hi:[1,0]
	v_pk_add_f32 v[194:195], v[194:195], 1.0 op_sel_hi:[1,0]
	v_div_scale_f32 v224, s[8:9], v192, v192, 1.0
	v_div_scale_f32 v229, s[8:9], v193, v193, 1.0
	v_div_scale_f32 v234, s[8:9], v194, v194, 1.0
	v_div_scale_f32 v239, s[8:9], v195, v195, 1.0
	v_div_scale_f32 v225, s[20:21], 1.0, v192, 1.0
	v_div_scale_f32 v230, s[22:23], 1.0, v193, 1.0
	v_div_scale_f32 v235, s[24:25], 1.0, v194, 1.0
	v_div_scale_f32 v240, s[26:27], 1.0, v195, 1.0
	v_rcp_f32_e32 v226, v224
	v_rcp_f32_e32 v231, v229
	v_rcp_f32_e32 v236, v234
	v_rcp_f32_e32 v241, v239
	v_fma_f32 v228, -v224, v226, 1.0
	v_fma_f32 v233, -v229, v231, 1.0
	v_fma_f32 v238, -v234, v236, 1.0
	v_fma_f32 v243, -v239, v241, 1.0
	v_fmac_f32_e32 v226, v228, v226
	v_fmac_f32_e32 v231, v233, v231
	v_fmac_f32_e32 v236, v238, v236
	v_fmac_f32_e32 v241, v243, v241
	v_mul_f32_e32 v227, v225, v226
	v_mul_f32_e32 v232, v230, v231
	v_mul_f32_e32 v237, v235, v236
	v_mul_f32_e32 v242, v240, v241
	v_fma_f32 v228, -v224, v227, v225
	v_fma_f32 v233, -v229, v232, v230
	v_fma_f32 v238, -v234, v237, v235
	v_fma_f32 v243, -v239, v242, v240
	v_fmac_f32_e32 v227, v228, v226
	v_fmac_f32_e32 v232, v233, v231
	v_fmac_f32_e32 v237, v238, v236
	v_fmac_f32_e32 v242, v243, v241
	v_fma_f32 v228, -v224, v227, v225
	v_fma_f32 v233, -v229, v232, v230
	v_fma_f32 v238, -v234, v237, v235
	v_fma_f32 v243, -v239, v242, v240
	s_mov_b64 vcc, s[20:21]
	s_nop 0
	v_div_fmas_f32 v228, v228, v226, v227
	s_mov_b64 vcc, s[22:23]
	s_nop 0
	v_div_fmas_f32 v233, v233, v231, v232
	s_mov_b64 vcc, s[24:25]
	s_nop 0
	v_div_fmas_f32 v238, v238, v236, v237
	s_mov_b64 vcc, s[26:27]
	s_nop 0
	v_div_fmas_f32 v243, v243, v241, v242
	v_div_fixup_f32 v196, v228, v192, 1.0
	v_div_fixup_f32 v197, v233, v193, 1.0
	v_div_fixup_f32 v198, v238, v194, 1.0
	v_div_fixup_f32 v199, v243, v195, 1.0
	v_pk_mul_f32 v[196:197], v[188:189], v[196:197]
	v_pk_mul_f32 v[198:199], v[190:191], v[198:199]
	v_pk_mul_f32 v[196:197], v[184:185], v[196:197]
	v_pk_mul_f32 v[198:199], v[186:187], v[198:199]
	v_cvt_pk_bf16_f32 v206, v196, v197
	v_cvt_pk_bf16_f32 v207, v198, v199
	v_add_u32_e32 v117, 0x2c00, v117
	global_store_dwordx2 v117, v[206:207], s[18:19]
	v_lshlrev_b32_e32 v160, 16, v22
	v_and_b32_e32 v161, 0xffff0000, v22
	v_lshlrev_b32_e32 v162, 16, v23
	v_and_b32_e32 v163, 0xffff0000, v23
	v_lshlrev_b32_e32 v172, 16, v38
	v_and_b32_e32 v173, 0xffff0000, v38
	v_lshlrev_b32_e32 v174, 16, v39
	v_and_b32_e32 v175, 0xffff0000, v39
	v_pk_mul_f32 v[184:185], v[72:73], v[168:169]
	v_pk_mul_f32 v[188:189], v[88:89], v[180:181]
	v_pk_mul_f32 v[186:187], v[74:75], v[170:171]
	v_pk_mul_f32 v[190:191], v[90:91], v[182:183]
	v_pk_fma_f32 v[184:185], v[76:77], v[164:165], v[184:185]
	v_pk_fma_f32 v[188:189], v[92:93], v[176:177], v[188:189]
	v_pk_fma_f32 v[186:187], v[78:79], v[166:167], v[186:187]
	v_pk_fma_f32 v[190:191], v[94:95], v[178:179], v[190:191]
	v_pk_fma_f32 v[184:185], v[80:81], v[160:161], v[184:185]
	v_pk_fma_f32 v[188:189], v[96:97], v[172:173], v[188:189]
	v_pk_fma_f32 v[186:187], v[82:83], v[162:163], v[186:187]
	v_pk_fma_f32 v[190:191], v[98:99], v[174:175], v[190:191]
	v_pk_add_f32 v[184:185], v[184:185], v[84:85]
	v_pk_add_f32 v[188:189], v[188:189], v[100:101]
	v_pk_add_f32 v[186:187], v[186:187], v[86:87]
	v_pk_add_f32 v[190:191], v[190:191], v[102:103]
	v_mul_f32_e32 v192, 0xbfb8aa3b, v188
	v_mul_f32_e32 v193, 0xbfb8aa3b, v189
	v_mul_f32_e32 v194, 0xbfb8aa3b, v190
	v_mul_f32_e32 v195, 0xbfb8aa3b, v191
	v_exp_f32_e32 v192, v192
	v_exp_f32_e32 v193, v193
	v_exp_f32_e32 v194, v194
	v_exp_f32_e32 v195, v195
	s_nop 0
	v_pk_add_f32 v[192:193], v[192:193], 1.0 op_sel_hi:[1,0]
	v_pk_add_f32 v[194:195], v[194:195], 1.0 op_sel_hi:[1,0]
	v_div_scale_f32 v224, s[8:9], v192, v192, 1.0
	v_div_scale_f32 v229, s[8:9], v193, v193, 1.0
	v_div_scale_f32 v234, s[8:9], v194, v194, 1.0
	v_div_scale_f32 v239, s[8:9], v195, v195, 1.0
	v_div_scale_f32 v225, s[20:21], 1.0, v192, 1.0
	v_div_scale_f32 v230, s[22:23], 1.0, v193, 1.0
	v_div_scale_f32 v235, s[24:25], 1.0, v194, 1.0
	v_div_scale_f32 v240, s[26:27], 1.0, v195, 1.0
	v_rcp_f32_e32 v226, v224
	v_rcp_f32_e32 v231, v229
	v_rcp_f32_e32 v236, v234
	v_rcp_f32_e32 v241, v239
	v_fma_f32 v228, -v224, v226, 1.0
	v_fma_f32 v233, -v229, v231, 1.0
	v_fma_f32 v238, -v234, v236, 1.0
	v_fma_f32 v243, -v239, v241, 1.0
	v_fmac_f32_e32 v226, v228, v226
	v_fmac_f32_e32 v231, v233, v231
	v_fmac_f32_e32 v236, v238, v236
	v_fmac_f32_e32 v241, v243, v241
	v_mul_f32_e32 v227, v225, v226
	v_mul_f32_e32 v232, v230, v231
	v_mul_f32_e32 v237, v235, v236
	v_mul_f32_e32 v242, v240, v241
	v_fma_f32 v228, -v224, v227, v225
	v_fma_f32 v233, -v229, v232, v230
	v_fma_f32 v238, -v234, v237, v235
	v_fma_f32 v243, -v239, v242, v240
	v_fmac_f32_e32 v227, v228, v226
	v_fmac_f32_e32 v232, v233, v231
	v_fmac_f32_e32 v237, v238, v236
	v_fmac_f32_e32 v242, v243, v241
	v_fma_f32 v228, -v224, v227, v225
	v_fma_f32 v233, -v229, v232, v230
	v_fma_f32 v238, -v234, v237, v235
	v_fma_f32 v243, -v239, v242, v240
	s_mov_b64 vcc, s[20:21]
	s_nop 0
	v_div_fmas_f32 v228, v228, v226, v227
	s_mov_b64 vcc, s[22:23]
	s_nop 0
	v_div_fmas_f32 v233, v233, v231, v232
	s_mov_b64 vcc, s[24:25]
	s_nop 0
	v_div_fmas_f32 v238, v238, v236, v237
	s_mov_b64 vcc, s[26:27]
	s_nop 0
	v_div_fmas_f32 v243, v243, v241, v242
	v_div_fixup_f32 v196, v228, v192, 1.0
	v_div_fixup_f32 v197, v233, v193, 1.0
	v_div_fixup_f32 v198, v238, v194, 1.0
	v_div_fixup_f32 v199, v243, v195, 1.0
	v_pk_mul_f32 v[196:197], v[188:189], v[196:197]
	v_pk_mul_f32 v[198:199], v[190:191], v[198:199]
	v_pk_mul_f32 v[196:197], v[184:185], v[196:197]
	v_pk_mul_f32 v[198:199], v[186:187], v[198:199]
	v_cvt_pk_bf16_f32 v208, v196, v197
	v_cvt_pk_bf16_f32 v209, v198, v199
	v_add_u32_e32 v117, 0x2c00, v117
	global_store_dwordx2 v117, v[208:209], s[18:19]
	v_mov_b32_e32 v111, v116
	s_mov_b64 exec, s[28:29]
	s_cbranch_execz .Lcv_next
	v_and_b32_e32 v5, 0x1ff, v111
	v_cmp_eq_u32_e32 vcc, 0, v5
	s_nop 1
	v_cndmask_b32_e32 v118, v20, v216, vcc
	v_cndmask_b32_e32 v119, v21, v216, vcc
	v_cndmask_b32_e32 v122, v36, v216, vcc
	v_cndmask_b32_e32 v123, v37, v216, vcc
	v_cndmask_b32_e32 v120, v22, v216, vcc
	v_cndmask_b32_e32 v121, v23, v216, vcc
	v_cndmask_b32_e32 v124, v38, v216, vcc
	v_cndmask_b32_e32 v125, v39, v216, vcc
	v_add_u32_e32 v116, 1, v111
	v_cmp_lt_u32_e32 vcc, v116, v112
	s_and_b64 s[28:29], vcc, exec
	s_nop 0
	v_cndmask_b32_e32 v108, v111, v116, vcc
	v_lshlrev_b32_e32 v5, 3, v108
	v_mul_u32_u24_e32 v6, 0x5800, v5
	v_add_u32_e32 v6, v6, v113
	v_mul_u32_u24_e32 v7, 0x2c00, v5
	v_add_u32_e32 v7, v7, v113
	v_mov_b32_e32 v117, v7
	global_load_dwordx2 v[8:9], v6, s[14:15]
	global_load_dwordx2 v[24:25], v6, s[16:17]
	v_add_u32_e32 v6, 0x5800, v6
	global_load_dwordx2 v[10:11], v6, s[14:15]
	global_load_dwordx2 v[26:27], v6, s[16:17]
	v_add_u32_e32 v6, 0x5800, v6
	global_load_dwordx2 v[12:13], v6, s[14:15]
	global_load_dwordx2 v[28:29], v6, s[16:17]
	v_add_u32_e32 v6, 0x5800, v6
	global_load_dwordx2 v[14:15], v6, s[14:15]
	global_load_dwordx2 v[30:31], v6, s[16:17]
	v_add_u32_e32 v6, 0x5800, v6
	global_load_dwordx2 v[16:17], v6, s[14:15]
	global_load_dwordx2 v[32:33], v6, s[16:17]
	v_add_u32_e32 v6, 0x5800, v6
	global_load_dwordx2 v[18:19], v6, s[14:15]
	global_load_dwordx2 v[34:35], v6, s[16:17]
	v_add_u32_e32 v6, 0x5800, v6
	global_load_dwordx2 v[20:21], v6, s[14:15]
	global_load_dwordx2 v[36:37], v6, s[16:17]
	v_add_u32_e32 v6, 0x5800, v6
	global_load_dwordx2 v[22:23], v6, s[14:15]
	global_load_dwordx2 v[38:39], v6, s[16:17]
	s_waitcnt vmcnt(24)
	v_lshlrev_b32_e32 v160, 16, v118
	v_and_b32_e32 v161, 0xffff0000, v118
	v_lshlrev_b32_e32 v162, 16, v119
	v_and_b32_e32 v163, 0xffff0000, v119
	v_lshlrev_b32_e32 v172, 16, v122
	v_and_b32_e32 v173, 0xffff0000, v122
	v_lshlrev_b32_e32 v174, 16, v123
	v_and_b32_e32 v175, 0xffff0000, v123
	v_lshlrev_b32_e32 v164, 16, v120
	v_and_b32_e32 v165, 0xffff0000, v120
	v_lshlrev_b32_e32 v166, 16, v121
	v_and_b32_e32 v167, 0xffff0000, v121
	v_lshlrev_b32_e32 v176, 16, v124
	v_and_b32_e32 v177, 0xffff0000, v124
	v_lshlrev_b32_e32 v178, 16, v125
	v_and_b32_e32 v179, 0xffff0000, v125
	v_lshlrev_b32_e32 v168, 16, v40
	v_and_b32_e32 v169, 0xffff0000, v40
	v_lshlrev_b32_e32 v170, 16, v41
	v_and_b32_e32 v171, 0xffff0000, v41
	v_lshlrev_b32_e32 v180, 16, v56
	v_and_b32_e32 v181, 0xffff0000, v56
	v_lshlrev_b32_e32 v182, 16, v57
	v_and_b32_e32 v183, 0xffff0000, v57
	v_pk_mul_f32 v[184:185], v[72:73], v[164:165]
	v_pk_mul_f32 v[188:189], v[88:89], v[176:177]
	v_pk_mul_f32 v[186:187], v[74:75], v[166:167]
	v_pk_mul_f32 v[190:191], v[90:91], v[178:179]
	v_pk_fma_f32 v[184:185], v[76:77], v[160:161], v[184:185]
	v_pk_fma_f32 v[188:189], v[92:93], v[172:173], v[188:189]
	v_pk_fma_f32 v[186:187], v[78:79], v[162:163], v[186:187]
	v_pk_fma_f32 v[190:191], v[94:95], v[174:175], v[190:191]
	v_pk_fma_f32 v[184:185], v[80:81], v[168:169], v[184:185]
	v_pk_fma_f32 v[188:189], v[96:97], v[180:181], v[188:189]
	v_pk_fma_f32 v[186:187], v[82:83], v[170:171], v[186:187]
	v_pk_fma_f32 v[190:191], v[98:99], v[182:183], v[190:191]
	v_pk_add_f32 v[184:185], v[184:185], v[84:85]
	v_pk_add_f32 v[188:189], v[188:189], v[100:101]
	v_pk_add_f32 v[186:187], v[186:187], v[86:87]
	v_pk_add_f32 v[190:191], v[190:191], v[102:103]
	v_mul_f32_e32 v192, 0xbfb8aa3b, v188
	v_mul_f32_e32 v193, 0xbfb8aa3b, v189
	v_mul_f32_e32 v194, 0xbfb8aa3b, v190
	v_mul_f32_e32 v195, 0xbfb8aa3b, v191
	v_exp_f32_e32 v192, v192
	v_exp_f32_e32 v193, v193
	v_exp_f32_e32 v194, v194
	v_exp_f32_e32 v195, v195
	s_nop 0
	v_pk_add_f32 v[192:193], v[192:193], 1.0 op_sel_hi:[1,0]
	v_pk_add_f32 v[194:195], v[194:195], 1.0 op_sel_hi:[1,0]
	v_div_scale_f32 v224, s[8:9], v192, v192, 1.0
	v_div_scale_f32 v229, s[8:9], v193, v193, 1.0
	v_div_scale_f32 v234, s[8:9], v194, v194, 1.0
	v_div_scale_f32 v239, s[8:9], v195, v195, 1.0
	v_div_scale_f32 v225, s[20:21], 1.0, v192, 1.0
	v_div_scale_f32 v230, s[22:23], 1.0, v193, 1.0
	v_div_scale_f32 v235, s[24:25], 1.0, v194, 1.0
	v_div_scale_f32 v240, s[26:27], 1.0, v195, 1.0
	v_rcp_f32_e32 v226, v224
	v_rcp_f32_e32 v231, v229
	v_rcp_f32_e32 v236, v234
	v_rcp_f32_e32 v241, v239
	v_fma_f32 v228, -v224, v226, 1.0
	v_fma_f32 v233, -v229, v231, 1.0
	v_fma_f32 v238, -v234, v236, 1.0
	v_fma_f32 v243, -v239, v241, 1.0
	v_fmac_f32_e32 v226, v228, v226
	v_fmac_f32_e32 v231, v233, v231
	v_fmac_f32_e32 v236, v238, v236
	v_fmac_f32_e32 v241, v243, v241
	v_mul_f32_e32 v227, v225, v226
	v_mul_f32_e32 v232, v230, v231
	v_mul_f32_e32 v237, v235, v236
	v_mul_f32_e32 v242, v240, v241
	v_fma_f32 v228, -v224, v227, v225
	v_fma_f32 v233, -v229, v232, v230
	v_fma_f32 v238, -v234, v237, v235
	v_fma_f32 v243, -v239, v242, v240
	v_fmac_f32_e32 v227, v228, v226
	v_fmac_f32_e32 v232, v233, v231
	v_fmac_f32_e32 v237, v238, v236
	v_fmac_f32_e32 v242, v243, v241
	v_fma_f32 v228, -v224, v227, v225
	v_fma_f32 v233, -v229, v232, v230
	v_fma_f32 v238, -v234, v237, v235
	v_fma_f32 v243, -v239, v242, v240
	s_mov_b64 vcc, s[20:21]
	s_nop 0
	v_div_fmas_f32 v228, v228, v226, v227
	s_mov_b64 vcc, s[22:23]
	s_nop 0
	v_div_fmas_f32 v233, v233, v231, v232
	s_mov_b64 vcc, s[24:25]
	s_nop 0
	v_div_fmas_f32 v238, v238, v236, v237
	s_mov_b64 vcc, s[26:27]
	s_nop 0
	v_div_fmas_f32 v243, v243, v241, v242
	v_div_fixup_f32 v196, v228, v192, 1.0
	v_div_fixup_f32 v197, v233, v193, 1.0
	v_div_fixup_f32 v198, v238, v194, 1.0
	v_div_fixup_f32 v199, v243, v195, 1.0
	v_pk_mul_f32 v[196:197], v[188:189], v[196:197]
	v_pk_mul_f32 v[198:199], v[190:191], v[198:199]
	v_pk_mul_f32 v[196:197], v[184:185], v[196:197]
	v_pk_mul_f32 v[198:199], v[186:187], v[198:199]
	v_cvt_pk_bf16_f32 v206, v196, v197
	v_cvt_pk_bf16_f32 v207, v198, v199
	global_store_dwordx2 v109, v[206:207], s[18:19]
	v_lshlrev_b32_e32 v160, 16, v42
	v_and_b32_e32 v161, 0xffff0000, v42
	v_lshlrev_b32_e32 v162, 16, v43
	v_and_b32_e32 v163, 0xffff0000, v43
	v_lshlrev_b32_e32 v172, 16, v58
	v_and_b32_e32 v173, 0xffff0000, v58
	v_lshlrev_b32_e32 v174, 16, v59
	v_and_b32_e32 v175, 0xffff0000, v59
	v_pk_mul_f32 v[184:185], v[72:73], v[168:169]
	v_pk_mul_f32 v[188:189], v[88:89], v[180:181]
	v_pk_mul_f32 v[186:187], v[74:75], v[170:171]
	v_pk_mul_f32 v[190:191], v[90:91], v[182:183]
	v_pk_fma_f32 v[184:185], v[76:77], v[164:165], v[184:185]
	v_pk_fma_f32 v[188:189], v[92:93], v[176:177], v[188:189]
	v_pk_fma_f32 v[186:187], v[78:79], v[166:167], v[186:187]
	v_pk_fma_f32 v[190:191], v[94:95], v[178:179], v[190:191]
	v_pk_fma_f32 v[184:185], v[80:81], v[160:161], v[184:185]
	v_pk_fma_f32 v[188:189], v[96:97], v[172:173], v[188:189]
	v_pk_fma_f32 v[186:187], v[82:83], v[162:163], v[186:187]
	v_pk_fma_f32 v[190:191], v[98:99], v[174:175], v[190:191]
	v_pk_add_f32 v[184:185], v[184:185], v[84:85]
	v_pk_add_f32 v[188:189], v[188:189], v[100:101]
	v_pk_add_f32 v[186:187], v[186:187], v[86:87]
	v_pk_add_f32 v[190:191], v[190:191], v[102:103]
	v_mul_f32_e32 v192, 0xbfb8aa3b, v188
	v_mul_f32_e32 v193, 0xbfb8aa3b, v189
	v_mul_f32_e32 v194, 0xbfb8aa3b, v190
	v_mul_f32_e32 v195, 0xbfb8aa3b, v191
	v_exp_f32_e32 v192, v192
	v_exp_f32_e32 v193, v193
	v_exp_f32_e32 v194, v194
	v_exp_f32_e32 v195, v195
	s_nop 0
	v_pk_add_f32 v[192:193], v[192:193], 1.0 op_sel_hi:[1,0]
	v_pk_add_f32 v[194:195], v[194:195], 1.0 op_sel_hi:[1,0]
	v_div_scale_f32 v224, s[8:9], v192, v192, 1.0
	v_div_scale_f32 v229, s[8:9], v193, v193, 1.0
	v_div_scale_f32 v234, s[8:9], v194, v194, 1.0
	v_div_scale_f32 v239, s[8:9], v195, v195, 1.0
	v_div_scale_f32 v225, s[20:21], 1.0, v192, 1.0
	v_div_scale_f32 v230, s[22:23], 1.0, v193, 1.0
	v_div_scale_f32 v235, s[24:25], 1.0, v194, 1.0
	v_div_scale_f32 v240, s[26:27], 1.0, v195, 1.0
	v_rcp_f32_e32 v226, v224
	v_rcp_f32_e32 v231, v229
	v_rcp_f32_e32 v236, v234
	v_rcp_f32_e32 v241, v239
	v_fma_f32 v228, -v224, v226, 1.0
	v_fma_f32 v233, -v229, v231, 1.0
	v_fma_f32 v238, -v234, v236, 1.0
	v_fma_f32 v243, -v239, v241, 1.0
	v_fmac_f32_e32 v226, v228, v226
	v_fmac_f32_e32 v231, v233, v231
	v_fmac_f32_e32 v236, v238, v236
	v_fmac_f32_e32 v241, v243, v241
	v_mul_f32_e32 v227, v225, v226
	v_mul_f32_e32 v232, v230, v231
	v_mul_f32_e32 v237, v235, v236
	v_mul_f32_e32 v242, v240, v241
	v_fma_f32 v228, -v224, v227, v225
	v_fma_f32 v233, -v229, v232, v230
	v_fma_f32 v238, -v234, v237, v235
	v_fma_f32 v243, -v239, v242, v240
	v_fmac_f32_e32 v227, v228, v226
	v_fmac_f32_e32 v232, v233, v231
	v_fmac_f32_e32 v237, v238, v236
	v_fmac_f32_e32 v242, v243, v241
	v_fma_f32 v228, -v224, v227, v225
	v_fma_f32 v233, -v229, v232, v230
	v_fma_f32 v238, -v234, v237, v235
	v_fma_f32 v243, -v239, v242, v240
	s_mov_b64 vcc, s[20:21]
	s_nop 0
	v_div_fmas_f32 v228, v228, v226, v227
	s_mov_b64 vcc, s[22:23]
	s_nop 0
	v_div_fmas_f32 v233, v233, v231, v232
	s_mov_b64 vcc, s[24:25]
	s_nop 0
	v_div_fmas_f32 v238, v238, v236, v237
	s_mov_b64 vcc, s[26:27]
	s_nop 0
	v_div_fmas_f32 v243, v243, v241, v242
	v_div_fixup_f32 v196, v228, v192, 1.0
	v_div_fixup_f32 v197, v233, v193, 1.0
	v_div_fixup_f32 v198, v238, v194, 1.0
	v_div_fixup_f32 v199, v243, v195, 1.0
	v_pk_mul_f32 v[196:197], v[188:189], v[196:197]
	v_pk_mul_f32 v[198:199], v[190:191], v[198:199]
	v_pk_mul_f32 v[196:197], v[184:185], v[196:197]
	v_pk_mul_f32 v[198:199], v[186:187], v[198:199]
	v_cvt_pk_bf16_f32 v208, v196, v197
	v_cvt_pk_bf16_f32 v209, v198, v199
	v_add_u32_e32 v109, 0x2c00, v109
	global_store_dwordx2 v109, v[208:209], s[18:19]
	v_lshlrev_b32_e32 v164, 16, v44
	v_and_b32_e32 v165, 0xffff0000, v44
	v_lshlrev_b32_e32 v166, 16, v45
	v_and_b32_e32 v167, 0xffff0000, v45
	v_lshlrev_b32_e32 v176, 16, v60
	v_and_b32_e32 v177, 0xffff0000, v60
	v_lshlrev_b32_e32 v178, 16, v61
	v_and_b32_e32 v179, 0xffff0000, v61
	v_pk_mul_f32 v[184:185], v[72:73], v[160:161]
	v_pk_mul_f32 v[188:189], v[88:89], v[172:173]
	v_pk_mul_f32 v[186:187], v[74:75], v[162:163]
	v_pk_mul_f32 v[190:191], v[90:91], v[174:175]
	v_pk_fma_f32 v[184:185], v[76:77], v[168:169], v[184:185]
	v_pk_fma_f32 v[188:189], v[92:93], v[180:181], v[188:189]
	v_pk_fma_f32 v[186:187], v[78:79], v[170:171], v[186:187]
	v_pk_fma_f32 v[190:191], v[94:95], v[182:183], v[190:191]
	v_pk_fma_f32 v[184:185], v[80:81], v[164:165], v[184:185]
	v_pk_fma_f32 v[188:189], v[96:97], v[176:177], v[188:189]
	v_pk_fma_f32 v[186:187], v[82:83], v[166:167], v[186:187]
	v_pk_fma_f32 v[190:191], v[98:99], v[178:179], v[190:191]
	v_pk_add_f32 v[184:185], v[184:185], v[84:85]
	v_pk_add_f32 v[188:189], v[188:189], v[100:101]
	v_pk_add_f32 v[186:187], v[186:187], v[86:87]
	v_pk_add_f32 v[190:191], v[190:191], v[102:103]
	v_mul_f32_e32 v192, 0xbfb8aa3b, v188
	v_mul_f32_e32 v193, 0xbfb8aa3b, v189
	v_mul_f32_e32 v194, 0xbfb8aa3b, v190
	v_mul_f32_e32 v195, 0xbfb8aa3b, v191
	v_exp_f32_e32 v192, v192
	v_exp_f32_e32 v193, v193
	v_exp_f32_e32 v194, v194
	v_exp_f32_e32 v195, v195
	s_nop 0
	v_pk_add_f32 v[192:193], v[192:193], 1.0 op_sel_hi:[1,0]
	v_pk_add_f32 v[194:195], v[194:195], 1.0 op_sel_hi:[1,0]
	v_div_scale_f32 v224, s[8:9], v192, v192, 1.0
	v_div_scale_f32 v229, s[8:9], v193, v193, 1.0
	v_div_scale_f32 v234, s[8:9], v194, v194, 1.0
	v_div_scale_f32 v239, s[8:9], v195, v195, 1.0
	v_div_scale_f32 v225, s[20:21], 1.0, v192, 1.0
	v_div_scale_f32 v230, s[22:23], 1.0, v193, 1.0
	v_div_scale_f32 v235, s[24:25], 1.0, v194, 1.0
	v_div_scale_f32 v240, s[26:27], 1.0, v195, 1.0
	v_rcp_f32_e32 v226, v224
	v_rcp_f32_e32 v231, v229
	v_rcp_f32_e32 v236, v234
	v_rcp_f32_e32 v241, v239
	v_fma_f32 v228, -v224, v226, 1.0
	v_fma_f32 v233, -v229, v231, 1.0
	v_fma_f32 v238, -v234, v236, 1.0
	v_fma_f32 v243, -v239, v241, 1.0
	v_fmac_f32_e32 v226, v228, v226
	v_fmac_f32_e32 v231, v233, v231
	v_fmac_f32_e32 v236, v238, v236
	v_fmac_f32_e32 v241, v243, v241
	v_mul_f32_e32 v227, v225, v226
	v_mul_f32_e32 v232, v230, v231
	v_mul_f32_e32 v237, v235, v236
	v_mul_f32_e32 v242, v240, v241
	v_fma_f32 v228, -v224, v227, v225
	v_fma_f32 v233, -v229, v232, v230
	v_fma_f32 v238, -v234, v237, v235
	v_fma_f32 v243, -v239, v242, v240
	v_fmac_f32_e32 v227, v228, v226
	v_fmac_f32_e32 v232, v233, v231
	v_fmac_f32_e32 v237, v238, v236
	v_fmac_f32_e32 v242, v243, v241
	v_fma_f32 v228, -v224, v227, v225
	v_fma_f32 v233, -v229, v232, v230
	v_fma_f32 v238, -v234, v237, v235
	v_fma_f32 v243, -v239, v242, v240
	s_mov_b64 vcc, s[20:21]
	s_nop 0
	v_div_fmas_f32 v228, v228, v226, v227
	s_mov_b64 vcc, s[22:23]
	s_nop 0
	v_div_fmas_f32 v233, v233, v231, v232
	s_mov_b64 vcc, s[24:25]
	s_nop 0
	v_div_fmas_f32 v238, v238, v236, v237
	s_mov_b64 vcc, s[26:27]
	s_nop 0
	v_div_fmas_f32 v243, v243, v241, v242
	v_div_fixup_f32 v196, v228, v192, 1.0
	v_div_fixup_f32 v197, v233, v193, 1.0
	v_div_fixup_f32 v198, v238, v194, 1.0
	v_div_fixup_f32 v199, v243, v195, 1.0
	v_pk_mul_f32 v[196:197], v[188:189], v[196:197]
	v_pk_mul_f32 v[198:199], v[190:191], v[198:199]
	v_pk_mul_f32 v[196:197], v[184:185], v[196:197]
	v_pk_mul_f32 v[198:199], v[186:187], v[198:199]
	v_cvt_pk_bf16_f32 v206, v196, v197
	v_cvt_pk_bf16_f32 v207, v198, v199
	v_add_u32_e32 v109, 0x2c00, v109
	global_store_dwordx2 v109, v[206:207], s[18:19]
	v_lshlrev_b32_e32 v168, 16, v46
	v_and_b32_e32 v169, 0xffff0000, v46
	v_lshlrev_b32_e32 v170, 16, v47
	v_and_b32_e32 v171, 0xffff0000, v47
	v_lshlrev_b32_e32 v180, 16, v62
	v_and_b32_e32 v181, 0xffff0000, v62
	v_lshlrev_b32_e32 v182, 16, v63
	v_and_b32_e32 v183, 0xffff0000, v63
	v_pk_mul_f32 v[184:185], v[72:73], v[164:165]
	v_pk_mul_f32 v[188:189], v[88:89], v[176:177]
	v_pk_mul_f32 v[186:187], v[74:75], v[166:167]
	v_pk_mul_f32 v[190:191], v[90:91], v[178:179]
	v_pk_fma_f32 v[184:185], v[76:77], v[160:161], v[184:185]
	v_pk_fma_f32 v[188:189], v[92:93], v[172:173], v[188:189]
	v_pk_fma_f32 v[186:187], v[78:79], v[162:163], v[186:187]
	v_pk_fma_f32 v[190:191], v[94:95], v[174:175], v[190:191]
	v_pk_fma_f32 v[184:185], v[80:81], v[168:169], v[184:185]
	v_pk_fma_f32 v[188:189], v[96:97], v[180:181], v[188:189]
	v_pk_fma_f32 v[186:187], v[82:83], v[170:171], v[186:187]
	v_pk_fma_f32 v[190:191], v[98:99], v[182:183], v[190:191]
	v_pk_add_f32 v[184:185], v[184:185], v[84:85]
	v_pk_add_f32 v[188:189], v[188:189], v[100:101]
	v_pk_add_f32 v[186:187], v[186:187], v[86:87]
	v_pk_add_f32 v[190:191], v[190:191], v[102:103]
	v_mul_f32_e32 v192, 0xbfb8aa3b, v188
	v_mul_f32_e32 v193, 0xbfb8aa3b, v189
	v_mul_f32_e32 v194, 0xbfb8aa3b, v190
	v_mul_f32_e32 v195, 0xbfb8aa3b, v191
	v_exp_f32_e32 v192, v192
	v_exp_f32_e32 v193, v193
	v_exp_f32_e32 v194, v194
	v_exp_f32_e32 v195, v195
	s_nop 0
	v_pk_add_f32 v[192:193], v[192:193], 1.0 op_sel_hi:[1,0]
	v_pk_add_f32 v[194:195], v[194:195], 1.0 op_sel_hi:[1,0]
	v_div_scale_f32 v224, s[8:9], v192, v192, 1.0
	v_div_scale_f32 v229, s[8:9], v193, v193, 1.0
	v_div_scale_f32 v234, s[8:9], v194, v194, 1.0
	v_div_scale_f32 v239, s[8:9], v195, v195, 1.0
	v_div_scale_f32 v225, s[20:21], 1.0, v192, 1.0
	v_div_scale_f32 v230, s[22:23], 1.0, v193, 1.0
	v_div_scale_f32 v235, s[24:25], 1.0, v194, 1.0
	v_div_scale_f32 v240, s[26:27], 1.0, v195, 1.0
	v_rcp_f32_e32 v226, v224
	v_rcp_f32_e32 v231, v229
	v_rcp_f32_e32 v236, v234
	v_rcp_f32_e32 v241, v239
	v_fma_f32 v228, -v224, v226, 1.0
	v_fma_f32 v233, -v229, v231, 1.0
	v_fma_f32 v238, -v234, v236, 1.0
	v_fma_f32 v243, -v239, v241, 1.0
	v_fmac_f32_e32 v226, v228, v226
	v_fmac_f32_e32 v231, v233, v231
	v_fmac_f32_e32 v236, v238, v236
	v_fmac_f32_e32 v241, v243, v241
	v_mul_f32_e32 v227, v225, v226
	v_mul_f32_e32 v232, v230, v231
	v_mul_f32_e32 v237, v235, v236
	v_mul_f32_e32 v242, v240, v241
	v_fma_f32 v228, -v224, v227, v225
	v_fma_f32 v233, -v229, v232, v230
	v_fma_f32 v238, -v234, v237, v235
	v_fma_f32 v243, -v239, v242, v240
	v_fmac_f32_e32 v227, v228, v226
	v_fmac_f32_e32 v232, v233, v231
	v_fmac_f32_e32 v237, v238, v236
	v_fmac_f32_e32 v242, v243, v241
	v_fma_f32 v228, -v224, v227, v225
	v_fma_f32 v233, -v229, v232, v230
	v_fma_f32 v238, -v234, v237, v235
	v_fma_f32 v243, -v239, v242, v240
	s_mov_b64 vcc, s[20:21]
	s_nop 0
	v_div_fmas_f32 v228, v228, v226, v227
	s_mov_b64 vcc, s[22:23]
	s_nop 0
	v_div_fmas_f32 v233, v233, v231, v232
	s_mov_b64 vcc, s[24:25]
	s_nop 0
	v_div_fmas_f32 v238, v238, v236, v237
	s_mov_b64 vcc, s[26:27]
	s_nop 0
	v_div_fmas_f32 v243, v243, v241, v242
	v_div_fixup_f32 v196, v228, v192, 1.0
	v_div_fixup_f32 v197, v233, v193, 1.0
	v_div_fixup_f32 v198, v238, v194, 1.0
	v_div_fixup_f32 v199, v243, v195, 1.0
	v_pk_mul_f32 v[196:197], v[188:189], v[196:197]
	v_pk_mul_f32 v[198:199], v[190:191], v[198:199]
	v_pk_mul_f32 v[196:197], v[184:185], v[196:197]
	v_pk_mul_f32 v[198:199], v[186:187], v[198:199]
	v_cvt_pk_bf16_f32 v208, v196, v197
	v_cvt_pk_bf16_f32 v209, v198, v199
	v_add_u32_e32 v109, 0x2c00, v109
	global_store_dwordx2 v109, v[208:209], s[18:19]
	v_lshlrev_b32_e32 v160, 16, v48
	v_and_b32_e32 v161, 0xffff0000, v48
	v_lshlrev_b32_e32 v162, 16, v49
	v_and_b32_e32 v163, 0xffff0000, v49
	v_lshlrev_b32_e32 v172, 16, v64
	v_and_b32_e32 v173, 0xffff0000, v64
	v_lshlrev_b32_e32 v174, 16, v65
	v_and_b32_e32 v175, 0xffff0000, v65
	v_pk_mul_f32 v[184:185], v[72:73], v[168:169]
	v_pk_mul_f32 v[188:189], v[88:89], v[180:181]
	v_pk_mul_f32 v[186:187], v[74:75], v[170:171]
	v_pk_mul_f32 v[190:191], v[90:91], v[182:183]
	v_pk_fma_f32 v[184:185], v[76:77], v[164:165], v[184:185]
	v_pk_fma_f32 v[188:189], v[92:93], v[176:177], v[188:189]
	v_pk_fma_f32 v[186:187], v[78:79], v[166:167], v[186:187]
	v_pk_fma_f32 v[190:191], v[94:95], v[178:179], v[190:191]
	v_pk_fma_f32 v[184:185], v[80:81], v[160:161], v[184:185]
	v_pk_fma_f32 v[188:189], v[96:97], v[172:173], v[188:189]
	v_pk_fma_f32 v[186:187], v[82:83], v[162:163], v[186:187]
	v_pk_fma_f32 v[190:191], v[98:99], v[174:175], v[190:191]
	v_pk_add_f32 v[184:185], v[184:185], v[84:85]
	v_pk_add_f32 v[188:189], v[188:189], v[100:101]
	v_pk_add_f32 v[186:187], v[186:187], v[86:87]
	v_pk_add_f32 v[190:191], v[190:191], v[102:103]
	v_mul_f32_e32 v192, 0xbfb8aa3b, v188
	v_mul_f32_e32 v193, 0xbfb8aa3b, v189
	v_mul_f32_e32 v194, 0xbfb8aa3b, v190
	v_mul_f32_e32 v195, 0xbfb8aa3b, v191
	v_exp_f32_e32 v192, v192
	v_exp_f32_e32 v193, v193
	v_exp_f32_e32 v194, v194
	v_exp_f32_e32 v195, v195
	s_nop 0
	v_pk_add_f32 v[192:193], v[192:193], 1.0 op_sel_hi:[1,0]
	v_pk_add_f32 v[194:195], v[194:195], 1.0 op_sel_hi:[1,0]
	v_div_scale_f32 v224, s[8:9], v192, v192, 1.0
	v_div_scale_f32 v229, s[8:9], v193, v193, 1.0
	v_div_scale_f32 v234, s[8:9], v194, v194, 1.0
	v_div_scale_f32 v239, s[8:9], v195, v195, 1.0
	v_div_scale_f32 v225, s[20:21], 1.0, v192, 1.0
	v_div_scale_f32 v230, s[22:23], 1.0, v193, 1.0
	v_div_scale_f32 v235, s[24:25], 1.0, v194, 1.0
	v_div_scale_f32 v240, s[26:27], 1.0, v195, 1.0
	v_rcp_f32_e32 v226, v224
	v_rcp_f32_e32 v231, v229
	v_rcp_f32_e32 v236, v234
	v_rcp_f32_e32 v241, v239
	v_fma_f32 v228, -v224, v226, 1.0
	v_fma_f32 v233, -v229, v231, 1.0
	v_fma_f32 v238, -v234, v236, 1.0
	v_fma_f32 v243, -v239, v241, 1.0
	v_fmac_f32_e32 v226, v228, v226
	v_fmac_f32_e32 v231, v233, v231
	v_fmac_f32_e32 v236, v238, v236
	v_fmac_f32_e32 v241, v243, v241
	v_mul_f32_e32 v227, v225, v226
	v_mul_f32_e32 v232, v230, v231
	v_mul_f32_e32 v237, v235, v236
	v_mul_f32_e32 v242, v240, v241
	v_fma_f32 v228, -v224, v227, v225
	v_fma_f32 v233, -v229, v232, v230
	v_fma_f32 v238, -v234, v237, v235
	v_fma_f32 v243, -v239, v242, v240
	v_fmac_f32_e32 v227, v228, v226
	v_fmac_f32_e32 v232, v233, v231
	v_fmac_f32_e32 v237, v238, v236
	v_fmac_f32_e32 v242, v243, v241
	v_fma_f32 v228, -v224, v227, v225
	v_fma_f32 v233, -v229, v232, v230
	v_fma_f32 v238, -v234, v237, v235
	v_fma_f32 v243, -v239, v242, v240
	s_mov_b64 vcc, s[20:21]
	s_nop 0
	v_div_fmas_f32 v228, v228, v226, v227
	s_mov_b64 vcc, s[22:23]
	s_nop 0
	v_div_fmas_f32 v233, v233, v231, v232
	s_mov_b64 vcc, s[24:25]
	s_nop 0
	v_div_fmas_f32 v238, v238, v236, v237
	s_mov_b64 vcc, s[26:27]
	s_nop 0
	v_div_fmas_f32 v243, v243, v241, v242
	v_div_fixup_f32 v196, v228, v192, 1.0
	v_div_fixup_f32 v197, v233, v193, 1.0
	v_div_fixup_f32 v198, v238, v194, 1.0
	v_div_fixup_f32 v199, v243, v195, 1.0
	v_pk_mul_f32 v[196:197], v[188:189], v[196:197]
	v_pk_mul_f32 v[198:199], v[190:191], v[198:199]
	v_pk_mul_f32 v[196:197], v[184:185], v[196:197]
	v_pk_mul_f32 v[198:199], v[186:187], v[198:199]
	v_cvt_pk_bf16_f32 v206, v196, v197
	v_cvt_pk_bf16_f32 v207, v198, v199
	v_add_u32_e32 v109, 0x2c00, v109
	global_store_dwordx2 v109, v[206:207], s[18:19]
	v_lshlrev_b32_e32 v164, 16, v50
	v_and_b32_e32 v165, 0xffff0000, v50
	v_lshlrev_b32_e32 v166, 16, v51
	v_and_b32_e32 v167, 0xffff0000, v51
	v_lshlrev_b32_e32 v176, 16, v66
	v_and_b32_e32 v177, 0xffff0000, v66
	v_lshlrev_b32_e32 v178, 16, v67
	v_and_b32_e32 v179, 0xffff0000, v67
	v_pk_mul_f32 v[184:185], v[72:73], v[160:161]
	v_pk_mul_f32 v[188:189], v[88:89], v[172:173]
	v_pk_mul_f32 v[186:187], v[74:75], v[162:163]
	v_pk_mul_f32 v[190:191], v[90:91], v[174:175]
	v_pk_fma_f32 v[184:185], v[76:77], v[168:169], v[184:185]
	v_pk_fma_f32 v[188:189], v[92:93], v[180:181], v[188:189]
	v_pk_fma_f32 v[186:187], v[78:79], v[170:171], v[186:187]
	v_pk_fma_f32 v[190:191], v[94:95], v[182:183], v[190:191]
	v_pk_fma_f32 v[184:185], v[80:81], v[164:165], v[184:185]
	v_pk_fma_f32 v[188:189], v[96:97], v[176:177], v[188:189]
	v_pk_fma_f32 v[186:187], v[82:83], v[166:167], v[186:187]
	v_pk_fma_f32 v[190:191], v[98:99], v[178:179], v[190:191]
	v_pk_add_f32 v[184:185], v[184:185], v[84:85]
	v_pk_add_f32 v[188:189], v[188:189], v[100:101]
	v_pk_add_f32 v[186:187], v[186:187], v[86:87]
	v_pk_add_f32 v[190:191], v[190:191], v[102:103]
	v_mul_f32_e32 v192, 0xbfb8aa3b, v188
	v_mul_f32_e32 v193, 0xbfb8aa3b, v189
	v_mul_f32_e32 v194, 0xbfb8aa3b, v190
	v_mul_f32_e32 v195, 0xbfb8aa3b, v191
	v_exp_f32_e32 v192, v192
	v_exp_f32_e32 v193, v193
	v_exp_f32_e32 v194, v194
	v_exp_f32_e32 v195, v195
	s_nop 0
	v_pk_add_f32 v[192:193], v[192:193], 1.0 op_sel_hi:[1,0]
	v_pk_add_f32 v[194:195], v[194:195], 1.0 op_sel_hi:[1,0]
	v_div_scale_f32 v224, s[8:9], v192, v192, 1.0
	v_div_scale_f32 v229, s[8:9], v193, v193, 1.0
	v_div_scale_f32 v234, s[8:9], v194, v194, 1.0
	v_div_scale_f32 v239, s[8:9], v195, v195, 1.0
	v_div_scale_f32 v225, s[20:21], 1.0, v192, 1.0
	v_div_scale_f32 v230, s[22:23], 1.0, v193, 1.0
	v_div_scale_f32 v235, s[24:25], 1.0, v194, 1.0
	v_div_scale_f32 v240, s[26:27], 1.0, v195, 1.0
	v_rcp_f32_e32 v226, v224
	v_rcp_f32_e32 v231, v229
	v_rcp_f32_e32 v236, v234
	v_rcp_f32_e32 v241, v239
	v_fma_f32 v228, -v224, v226, 1.0
	v_fma_f32 v233, -v229, v231, 1.0
	v_fma_f32 v238, -v234, v236, 1.0
	v_fma_f32 v243, -v239, v241, 1.0
	v_fmac_f32_e32 v226, v228, v226
	v_fmac_f32_e32 v231, v233, v231
	v_fmac_f32_e32 v236, v238, v236
	v_fmac_f32_e32 v241, v243, v241
	v_mul_f32_e32 v227, v225, v226
	v_mul_f32_e32 v232, v230, v231
	v_mul_f32_e32 v237, v235, v236
	v_mul_f32_e32 v242, v240, v241
	v_fma_f32 v228, -v224, v227, v225
	v_fma_f32 v233, -v229, v232, v230
	v_fma_f32 v238, -v234, v237, v235
	v_fma_f32 v243, -v239, v242, v240
	v_fmac_f32_e32 v227, v228, v226
	v_fmac_f32_e32 v232, v233, v231
	v_fmac_f32_e32 v237, v238, v236
	v_fmac_f32_e32 v242, v243, v241
	v_fma_f32 v228, -v224, v227, v225
	v_fma_f32 v233, -v229, v232, v230
	v_fma_f32 v238, -v234, v237, v235
	v_fma_f32 v243, -v239, v242, v240
	s_mov_b64 vcc, s[20:21]
	s_nop 0
	v_div_fmas_f32 v228, v228, v226, v227
	s_mov_b64 vcc, s[22:23]
	s_nop 0
	v_div_fmas_f32 v233, v233, v231, v232
	s_mov_b64 vcc, s[24:25]
	s_nop 0
	v_div_fmas_f32 v238, v238, v236, v237
	s_mov_b64 vcc, s[26:27]
	s_nop 0
	v_div_fmas_f32 v243, v243, v241, v242
	v_div_fixup_f32 v196, v228, v192, 1.0
	v_div_fixup_f32 v197, v233, v193, 1.0
	v_div_fixup_f32 v198, v238, v194, 1.0
	v_div_fixup_f32 v199, v243, v195, 1.0
	v_pk_mul_f32 v[196:197], v[188:189], v[196:197]
	v_pk_mul_f32 v[198:199], v[190:191], v[198:199]
	v_pk_mul_f32 v[196:197], v[184:185], v[196:197]
	v_pk_mul_f32 v[198:199], v[186:187], v[198:199]
	v_cvt_pk_bf16_f32 v208, v196, v197
	v_cvt_pk_bf16_f32 v209, v198, v199
	v_add_u32_e32 v109, 0x2c00, v109
	global_store_dwordx2 v109, v[208:209], s[18:19]
	v_lshlrev_b32_e32 v168, 16, v52
	v_and_b32_e32 v169, 0xffff0000, v52
	v_lshlrev_b32_e32 v170, 16, v53
	v_and_b32_e32 v171, 0xffff0000, v53
	v_lshlrev_b32_e32 v180, 16, v68
	v_and_b32_e32 v181, 0xffff0000, v68
	v_lshlrev_b32_e32 v182, 16, v69
	v_and_b32_e32 v183, 0xffff0000, v69
	v_pk_mul_f32 v[184:185], v[72:73], v[164:165]
	v_pk_mul_f32 v[188:189], v[88:89], v[176:177]
	v_pk_mul_f32 v[186:187], v[74:75], v[166:167]
	v_pk_mul_f32 v[190:191], v[90:91], v[178:179]
	v_pk_fma_f32 v[184:185], v[76:77], v[160:161], v[184:185]
	v_pk_fma_f32 v[188:189], v[92:93], v[172:173], v[188:189]
	v_pk_fma_f32 v[186:187], v[78:79], v[162:163], v[186:187]
	v_pk_fma_f32 v[190:191], v[94:95], v[174:175], v[190:191]
	v_pk_fma_f32 v[184:185], v[80:81], v[168:169], v[184:185]
	v_pk_fma_f32 v[188:189], v[96:97], v[180:181], v[188:189]
	v_pk_fma_f32 v[186:187], v[82:83], v[170:171], v[186:187]
	v_pk_fma_f32 v[190:191], v[98:99], v[182:183], v[190:191]
	v_pk_add_f32 v[184:185], v[184:185], v[84:85]
	v_pk_add_f32 v[188:189], v[188:189], v[100:101]
	v_pk_add_f32 v[186:187], v[186:187], v[86:87]
	v_pk_add_f32 v[190:191], v[190:191], v[102:103]
	v_mul_f32_e32 v192, 0xbfb8aa3b, v188
	v_mul_f32_e32 v193, 0xbfb8aa3b, v189
	v_mul_f32_e32 v194, 0xbfb8aa3b, v190
	v_mul_f32_e32 v195, 0xbfb8aa3b, v191
	v_exp_f32_e32 v192, v192
	v_exp_f32_e32 v193, v193
	v_exp_f32_e32 v194, v194
	v_exp_f32_e32 v195, v195
	s_nop 0
	v_pk_add_f32 v[192:193], v[192:193], 1.0 op_sel_hi:[1,0]
	v_pk_add_f32 v[194:195], v[194:195], 1.0 op_sel_hi:[1,0]
	v_div_scale_f32 v224, s[8:9], v192, v192, 1.0
	v_div_scale_f32 v229, s[8:9], v193, v193, 1.0
	v_div_scale_f32 v234, s[8:9], v194, v194, 1.0
	v_div_scale_f32 v239, s[8:9], v195, v195, 1.0
	v_div_scale_f32 v225, s[20:21], 1.0, v192, 1.0
	v_div_scale_f32 v230, s[22:23], 1.0, v193, 1.0
	v_div_scale_f32 v235, s[24:25], 1.0, v194, 1.0
	v_div_scale_f32 v240, s[26:27], 1.0, v195, 1.0
	v_rcp_f32_e32 v226, v224
	v_rcp_f32_e32 v231, v229
	v_rcp_f32_e32 v236, v234
	v_rcp_f32_e32 v241, v239
	v_fma_f32 v228, -v224, v226, 1.0
	v_fma_f32 v233, -v229, v231, 1.0
	v_fma_f32 v238, -v234, v236, 1.0
	v_fma_f32 v243, -v239, v241, 1.0
	v_fmac_f32_e32 v226, v228, v226
	v_fmac_f32_e32 v231, v233, v231
	v_fmac_f32_e32 v236, v238, v236
	v_fmac_f32_e32 v241, v243, v241
	v_mul_f32_e32 v227, v225, v226
	v_mul_f32_e32 v232, v230, v231
	v_mul_f32_e32 v237, v235, v236
	v_mul_f32_e32 v242, v240, v241
	v_fma_f32 v228, -v224, v227, v225
	v_fma_f32 v233, -v229, v232, v230
	v_fma_f32 v238, -v234, v237, v235
	v_fma_f32 v243, -v239, v242, v240
	v_fmac_f32_e32 v227, v228, v226
	v_fmac_f32_e32 v232, v233, v231
	v_fmac_f32_e32 v237, v238, v236
	v_fmac_f32_e32 v242, v243, v241
	v_fma_f32 v228, -v224, v227, v225
	v_fma_f32 v233, -v229, v232, v230
	v_fma_f32 v238, -v234, v237, v235
	v_fma_f32 v243, -v239, v242, v240
	s_mov_b64 vcc, s[20:21]
	s_nop 0
	v_div_fmas_f32 v228, v228, v226, v227
	s_mov_b64 vcc, s[22:23]
	s_nop 0
	v_div_fmas_f32 v233, v233, v231, v232
	s_mov_b64 vcc, s[24:25]
	s_nop 0
	v_div_fmas_f32 v238, v238, v236, v237
	s_mov_b64 vcc, s[26:27]
	s_nop 0
	v_div_fmas_f32 v243, v243, v241, v242
	v_div_fixup_f32 v196, v228, v192, 1.0
	v_div_fixup_f32 v197, v233, v193, 1.0
	v_div_fixup_f32 v198, v238, v194, 1.0
	v_div_fixup_f32 v199, v243, v195, 1.0
	v_pk_mul_f32 v[196:197], v[188:189], v[196:197]
	v_pk_mul_f32 v[198:199], v[190:191], v[198:199]
	v_pk_mul_f32 v[196:197], v[184:185], v[196:197]
	v_pk_mul_f32 v[198:199], v[186:187], v[198:199]
	v_cvt_pk_bf16_f32 v206, v196, v197
	v_cvt_pk_bf16_f32 v207, v198, v199
	v_add_u32_e32 v109, 0x2c00, v109
	global_store_dwordx2 v109, v[206:207], s[18:19]
	v_lshlrev_b32_e32 v160, 16, v54
	v_and_b32_e32 v161, 0xffff0000, v54
	v_lshlrev_b32_e32 v162, 16, v55
	v_and_b32_e32 v163, 0xffff0000, v55
	v_lshlrev_b32_e32 v172, 16, v70
	v_and_b32_e32 v173, 0xffff0000, v70
	v_lshlrev_b32_e32 v174, 16, v71
	v_and_b32_e32 v175, 0xffff0000, v71
	v_pk_mul_f32 v[184:185], v[72:73], v[168:169]
	v_pk_mul_f32 v[188:189], v[88:89], v[180:181]
	v_pk_mul_f32 v[186:187], v[74:75], v[170:171]
	v_pk_mul_f32 v[190:191], v[90:91], v[182:183]
	v_pk_fma_f32 v[184:185], v[76:77], v[164:165], v[184:185]
	v_pk_fma_f32 v[188:189], v[92:93], v[176:177], v[188:189]
	v_pk_fma_f32 v[186:187], v[78:79], v[166:167], v[186:187]
	v_pk_fma_f32 v[190:191], v[94:95], v[178:179], v[190:191]
	v_pk_fma_f32 v[184:185], v[80:81], v[160:161], v[184:185]
	v_pk_fma_f32 v[188:189], v[96:97], v[172:173], v[188:189]
	v_pk_fma_f32 v[186:187], v[82:83], v[162:163], v[186:187]
	v_pk_fma_f32 v[190:191], v[98:99], v[174:175], v[190:191]
	v_pk_add_f32 v[184:185], v[184:185], v[84:85]
	v_pk_add_f32 v[188:189], v[188:189], v[100:101]
	v_pk_add_f32 v[186:187], v[186:187], v[86:87]
	v_pk_add_f32 v[190:191], v[190:191], v[102:103]
	v_mul_f32_e32 v192, 0xbfb8aa3b, v188
	v_mul_f32_e32 v193, 0xbfb8aa3b, v189
	v_mul_f32_e32 v194, 0xbfb8aa3b, v190
	v_mul_f32_e32 v195, 0xbfb8aa3b, v191
	v_exp_f32_e32 v192, v192
	v_exp_f32_e32 v193, v193
	v_exp_f32_e32 v194, v194
	v_exp_f32_e32 v195, v195
	s_nop 0
	v_pk_add_f32 v[192:193], v[192:193], 1.0 op_sel_hi:[1,0]
	v_pk_add_f32 v[194:195], v[194:195], 1.0 op_sel_hi:[1,0]
	v_div_scale_f32 v224, s[8:9], v192, v192, 1.0
	v_div_scale_f32 v229, s[8:9], v193, v193, 1.0
	v_div_scale_f32 v234, s[8:9], v194, v194, 1.0
	v_div_scale_f32 v239, s[8:9], v195, v195, 1.0
	v_div_scale_f32 v225, s[20:21], 1.0, v192, 1.0
	v_div_scale_f32 v230, s[22:23], 1.0, v193, 1.0
	v_div_scale_f32 v235, s[24:25], 1.0, v194, 1.0
	v_div_scale_f32 v240, s[26:27], 1.0, v195, 1.0
	v_rcp_f32_e32 v226, v224
	v_rcp_f32_e32 v231, v229
	v_rcp_f32_e32 v236, v234
	v_rcp_f32_e32 v241, v239
	v_fma_f32 v228, -v224, v226, 1.0
	v_fma_f32 v233, -v229, v231, 1.0
	v_fma_f32 v238, -v234, v236, 1.0
	v_fma_f32 v243, -v239, v241, 1.0
	v_fmac_f32_e32 v226, v228, v226
	v_fmac_f32_e32 v231, v233, v231
	v_fmac_f32_e32 v236, v238, v236
	v_fmac_f32_e32 v241, v243, v241
	v_mul_f32_e32 v227, v225, v226
	v_mul_f32_e32 v232, v230, v231
	v_mul_f32_e32 v237, v235, v236
	v_mul_f32_e32 v242, v240, v241
	v_fma_f32 v228, -v224, v227, v225
	v_fma_f32 v233, -v229, v232, v230
	v_fma_f32 v238, -v234, v237, v235
	v_fma_f32 v243, -v239, v242, v240
	v_fmac_f32_e32 v227, v228, v226
	v_fmac_f32_e32 v232, v233, v231
	v_fmac_f32_e32 v237, v238, v236
	v_fmac_f32_e32 v242, v243, v241
	v_fma_f32 v228, -v224, v227, v225
	v_fma_f32 v233, -v229, v232, v230
	v_fma_f32 v238, -v234, v237, v235
	v_fma_f32 v243, -v239, v242, v240
	s_mov_b64 vcc, s[20:21]
	s_nop 0
	v_div_fmas_f32 v228, v228, v226, v227
	s_mov_b64 vcc, s[22:23]
	s_nop 0
	v_div_fmas_f32 v233, v233, v231, v232
	s_mov_b64 vcc, s[24:25]
	s_nop 0
	v_div_fmas_f32 v238, v238, v236, v237
	s_mov_b64 vcc, s[26:27]
	s_nop 0
	v_div_fmas_f32 v243, v243, v241, v242
	v_div_fixup_f32 v196, v228, v192, 1.0
	v_div_fixup_f32 v197, v233, v193, 1.0
	v_div_fixup_f32 v198, v238, v194, 1.0
	v_div_fixup_f32 v199, v243, v195, 1.0
	v_pk_mul_f32 v[196:197], v[188:189], v[196:197]
	v_pk_mul_f32 v[198:199], v[190:191], v[198:199]
	v_pk_mul_f32 v[196:197], v[184:185], v[196:197]
	v_pk_mul_f32 v[198:199], v[186:187], v[198:199]
	v_cvt_pk_bf16_f32 v208, v196, v197
	v_cvt_pk_bf16_f32 v209, v198, v199
	v_add_u32_e32 v109, 0x2c00, v109
	global_store_dwordx2 v109, v[208:209], s[18:19]
	v_mov_b32_e32 v111, v116
	s_mov_b64 exec, s[28:29]
	s_cbranch_execz .Lcv_next
	s_branch .Lcv_loop
.Lcv_next:
	s_mov_b64 exec, s[6:7]
	v_add_u32_e32 v110, s3, v110
	s_mov_b32 s39, 0x1d900
	v_cmp_gt_u32_e32 vcc, s39, v110
	s_and_b64 exec, exec, vcc
	s_cbranch_execnz .Lcv_task
